# GEMM K-loops (6 copies): first half-step LDS-DMA issues woven into the MFMA stream after the second barrier (def-use checked reorder + hazard nops)
# speedup vs baseline: 1.0670x; 1.0220x over previous
.LBB0_134:
	s_mul_i32 s17, s16, 0x6000
	v_add_u32_e32 v146, s17, v145
	v_add_u32_e32 v147, s17, v143
	v_add_u32_e32 v198, v146, v141
	v_add_u32_e32 v199, v147, v141
	v_add_u32_e32 v200, v146, v142
	v_add_u32_e32 v201, v147, v142
	s_waitcnt vmcnt(6)
	s_barrier
	ds_read_b128 v[146:149], v198
	ds_read_b128 v[150:153], v198 offset:2048
	ds_read_b128 v[154:157], v199
	ds_read_b128 v[158:161], v199 offset:2048
	ds_read_b128 v[162:165], v199 offset:4096
	ds_read_b128 v[170:173], v199 offset:6144
	ds_read_b128 v[174:177], v200
	ds_read_b128 v[178:181], v200 offset:2048
	ds_read_b128 v[182:185], v201
	ds_read_b128 v[186:189], v201 offset:2048
	ds_read_b128 v[190:193], v201 offset:4096
	ds_read_b128 v[194:197], v201 offset:6144
	s_waitcnt lgkmcnt(0)
	v_mfma_f32_32x32x16_bf16 v[114:129], v[146:149], v[154:157], v[114:129]
	s_waitcnt vmcnt(0)
	s_barrier
	v_mfma_f32_32x32x16_bf16 v[82:97], v[146:149], v[158:161], v[82:97]
	v_mfma_f32_32x32x16_bf16 v[50:65], v[146:149], v[162:165], v[50:65]
	v_mfma_f32_32x32x16_bf16 v[18:33], v[146:149], v[170:173], v[18:33]
	s_add_i32 s18, s17, 0xffffa000
	s_cmp_gt_i32 s16, 0
	s_cselect_b32 s18, s18, 0xc000
	v_add_u32_e32 v148, s18, v139
	v_lshl_add_u64 v[136:137], v[132:133], 0, v[0:1]
	v_readfirstlane_b32 s18, v148
	v_add_u32_e32 v146, 0x1000, v148
	v_lshl_add_u64 v[134:135], v[136:137], 0, s[24:25]
	s_mov_b32 m0, s18
	v_readfirstlane_b32 s18, v146
	v_add_u32_e32 v146, 0x2000, v148
	global_load_lds_dwordx4 v[134:135], off
	v_mfma_f32_32x32x16_bf16 v[98:113], v[150:153], v[154:157], v[98:113]
	v_lshl_add_u64 v[134:135], v[136:137], 0, s[36:37]
	s_mov_b32 m0, s18
	v_readfirstlane_b32 s18, v146
	v_add_u32_e32 v146, 0x3000, v148
	global_load_lds_dwordx4 v[134:135], off
	v_mfma_f32_32x32x16_bf16 v[66:81], v[150:153], v[158:161], v[66:81]
	v_lshl_add_u64 v[134:135], v[136:137], 0, s[38:39]
	s_mov_b32 m0, s18
	v_readfirstlane_b32 s18, v146
	global_load_lds_dwordx4 v[134:135], off
	v_mfma_f32_32x32x16_bf16 v[34:49], v[150:153], v[162:165], v[34:49]
	v_lshl_add_u64 v[134:135], v[136:137], 0, s[40:41]
	s_mov_b32 m0, s18
	v_add_u32_e32 v149, 0x4000, v148
	global_load_lds_dwordx4 v[134:135], off
	v_mfma_f32_32x32x16_bf16 v[2:17], v[150:153], v[170:173], v[2:17]
	v_lshl_add_u64 v[134:135], v[130:131], 0, v[0:1]
	v_readfirstlane_b32 s18, v149
	v_lshl_add_u64 v[146:147], v[134:135], 0, s[44:45]
	s_mov_b32 m0, s18
	s_mov_b64 s[18:19], 0x71000
	v_add_u32_e32 v148, 0x5000, v148
	global_load_lds_dwordx4 v[146:147], off
	v_mfma_f32_32x32x16_bf16 v[114:129], v[174:177], v[182:185], v[114:129]
	v_lshl_add_u64 v[146:147], v[134:135], 0, s[18:19]
	v_readfirstlane_b32 s18, v148
	s_mov_b32 m0, s18
	v_lshl_add_u64 v[130:131], v[130:131], 0, s[44:45]
	global_load_lds_dwordx4 v[146:147], off
	v_mfma_f32_32x32x16_bf16 v[98:113], v[178:181], v[182:185], v[98:113]
	s_add_i32 s17, s16, 1
	s_cmp_lg_u32 s16, 2
	s_cselect_b32 s16, s17, 0
	s_mul_i32 s17, s16, 0x6000
	s_add_i32 s18, s17, 0xffffa000
	s_cmp_gt_i32 s16, 0
	s_cselect_b32 s18, s18, 0xc000
	v_lshl_add_u64 v[132:133], v[132:133], 0, s[96:97]
	v_add_u32_e32 v148, s18, v139
	v_add_u32_e32 v149, 0x1000, v148
	v_readfirstlane_b32 s18, v148
	v_lshl_add_u64 v[146:147], v[136:137], 0, s[88:89]
	s_mov_b32 m0, s18
	v_readfirstlane_b32 s18, v149
	v_add_u32_e32 v149, 0x2000, v148
	global_load_lds_dwordx4 v[146:147], off
	v_mfma_f32_32x32x16_bf16 v[82:97], v[174:177], v[186:189], v[82:97]
	v_lshl_add_u64 v[146:147], v[136:137], 0, s[4:5]
	s_mov_b32 m0, s18
	v_readfirstlane_b32 s18, v149
	global_load_lds_dwordx4 v[146:147], off
	v_mfma_f32_32x32x16_bf16 v[66:81], v[178:181], v[186:189], v[66:81]
	v_lshl_add_u64 v[146:147], v[136:137], 0, s[84:85]
	s_mov_b32 m0, s18
	v_lshl_add_u64 v[136:137], v[136:137], 0, s[86:87]
	global_load_lds_dwordx4 v[146:147], off
	v_mfma_f32_32x32x16_bf16 v[50:65], v[174:177], v[190:193], v[50:65]
	v_add_u32_e32 v146, 0x3000, v148
	s_nop 0
	v_readfirstlane_b32 s18, v146
	s_mov_b32 m0, s18
	s_mov_b64 s[18:19], 0xa8000
	v_add_u32_e32 v146, 0x4000, v148
	global_load_lds_dwordx4 v[136:137], off
	v_mfma_f32_32x32x16_bf16 v[34:49], v[178:181], v[190:193], v[34:49]
	v_lshl_add_u64 v[136:137], v[134:135], 0, s[18:19]
	v_readfirstlane_b32 s18, v146
	s_mov_b32 m0, s18
	s_mov_b64 s[18:19], 0xa9000
	global_load_lds_dwordx4 v[136:137], off
	v_mfma_f32_32x32x16_bf16 v[18:33], v[174:177], v[194:197], v[18:33]
	v_add_u32_e32 v136, 0x5000, v148
	v_lshl_add_u64 v[134:135], v[134:135], 0, s[18:19]
	v_readfirstlane_b32 s18, v136
	s_mov_b32 m0, s18
	s_nop 0
	global_load_lds_dwordx4 v[134:135], off
	v_mfma_f32_32x32x16_bf16 v[2:17], v[178:181], v[194:197], v[2:17]
	v_add_u32_e32 v134, s17, v145
	v_add_u32_e32 v135, s17, v143
	s_add_i32 s17, s16, 1
	s_cmp_lg_u32 s16, 2
	s_cselect_b32 s16, s17, 0
	s_add_i32 s15, s15, -2
	s_cmp_eq_u32 s15, 0
	v_add_u32_e32 v194, v134, v141
	v_add_u32_e32 v195, v135, v141
	v_add_u32_e32 v196, v134, v142
	v_add_u32_e32 v197, v135, v142
	ds_read_b128 v[134:137], v194
	ds_read_b128 v[146:149], v194 offset:2048
	ds_read_b128 v[150:153], v195
	ds_read_b128 v[154:157], v195 offset:2048
	ds_read_b128 v[158:161], v195 offset:4096
	ds_read_b128 v[162:165], v195 offset:6144
	ds_read_b128 v[170:173], v196
	ds_read_b128 v[174:177], v196 offset:2048
	ds_read_b128 v[178:181], v197
	ds_read_b128 v[182:185], v197 offset:2048
	ds_read_b128 v[186:189], v197 offset:4096
	ds_read_b128 v[190:193], v197 offset:6144
	s_waitcnt lgkmcnt(0)
	s_nop 0
	v_mfma_f32_32x32x16_bf16 v[114:129], v[134:137], v[150:153], v[114:129]
	v_mfma_f32_32x32x16_bf16 v[98:113], v[146:149], v[150:153], v[98:113]
	v_mfma_f32_32x32x16_bf16 v[82:97], v[134:137], v[154:157], v[82:97]
	v_mfma_f32_32x32x16_bf16 v[66:81], v[146:149], v[154:157], v[66:81]
	v_mfma_f32_32x32x16_bf16 v[50:65], v[134:137], v[158:161], v[50:65]
	v_mfma_f32_32x32x16_bf16 v[34:49], v[146:149], v[158:161], v[34:49]
	v_mfma_f32_32x32x16_bf16 v[18:33], v[134:137], v[162:165], v[18:33]
	v_mfma_f32_32x32x16_bf16 v[2:17], v[146:149], v[162:165], v[2:17]
	v_mfma_f32_32x32x16_bf16 v[114:129], v[170:173], v[178:181], v[114:129]
	v_mfma_f32_32x32x16_bf16 v[98:113], v[174:177], v[178:181], v[98:113]
	v_mfma_f32_32x32x16_bf16 v[82:97], v[170:173], v[182:185], v[82:97]
	v_mfma_f32_32x32x16_bf16 v[66:81], v[174:177], v[182:185], v[66:81]
	v_mfma_f32_32x32x16_bf16 v[50:65], v[170:173], v[186:189], v[50:65]
	v_mfma_f32_32x32x16_bf16 v[34:49], v[174:177], v[186:189], v[34:49]
	v_mfma_f32_32x32x16_bf16 v[18:33], v[170:173], v[190:193], v[18:33]
	v_mfma_f32_32x32x16_bf16 v[2:17], v[174:177], v[190:193], v[2:17]
	s_cbranch_scc0 .LBB0_134
	s_waitcnt vmcnt(6)
	s_barrier
	v_add_u32_e32 v0, v145, v141
	v_add_u32_e32 v190, v143, v141
	v_add_u32_e32 v145, v145, v142
	v_add_u32_e32 v191, v143, v142
	ds_read_b128 v[130:133], v0
	ds_read_b128 v[134:137], v0 offset:2048
	ds_read_b128 v[146:149], v190
	ds_read_b128 v[150:153], v190 offset:2048
	ds_read_b128 v[154:157], v190 offset:4096
	ds_read_b128 v[158:161], v190 offset:6144
	ds_read_b128 v[162:165], v145
	ds_read_b128 v[170:173], v145 offset:2048
	ds_read_b128 v[174:177], v191
	ds_read_b128 v[178:181], v191 offset:2048
	ds_read_b128 v[182:185], v191 offset:4096
	ds_read_b128 v[186:189], v191 offset:6144
	s_waitcnt lgkmcnt(0)
	v_or_b32_e32 v0, 0xa000, v144
	v_mfma_f32_32x32x16_bf16 v[50:65], v[130:133], v[154:157], v[50:65]
	s_waitcnt vmcnt(0)
	s_barrier
	s_lshl_b32 s15, s14, 1
	v_mfma_f32_32x32x16_bf16 v[34:49], v[134:137], v[154:157], v[34:49]
	v_mfma_f32_32x32x16_bf16 v[82:97], v[130:133], v[150:153], v[82:97]
	v_mfma_f32_32x32x16_bf16 v[66:81], v[134:137], v[150:153], v[66:81]
	v_mfma_f32_32x32x16_bf16 v[2:17], v[134:137], v[158:161], v[2:17]
	v_mfma_f32_32x32x16_bf16 v[114:129], v[130:133], v[146:149], v[114:129]
	v_mfma_f32_32x32x16_bf16 v[98:113], v[134:137], v[146:149], v[98:113]
	v_mfma_f32_32x32x16_bf16 v[18:33], v[130:133], v[158:161], v[18:33]
	v_add_u32_e32 v130, 0x6000, v143
	v_mfma_f32_32x32x16_bf16 v[50:65], v[162:165], v[182:185], v[50:65]
	v_mfma_f32_32x32x16_bf16 v[34:49], v[170:173], v[182:185], v[34:49]
	v_mfma_f32_32x32x16_bf16 v[82:97], v[162:165], v[178:181], v[82:97]
	v_mfma_f32_32x32x16_bf16 v[66:81], v[170:173], v[178:181], v[66:81]
	v_mfma_f32_32x32x16_bf16 v[2:17], v[170:173], v[186:189], v[2:17]
	v_mfma_f32_32x32x16_bf16 v[114:129], v[162:165], v[174:177], v[114:129]
	v_mfma_f32_32x32x16_bf16 v[98:113], v[170:173], v[174:177], v[98:113]
	v_mfma_f32_32x32x16_bf16 v[18:33], v[162:165], v[186:189], v[18:33]
	v_add_u32_e32 v186, v141, v0
	v_add_u32_e32 v141, v141, v130
	v_add_u32_e32 v0, v142, v0
	v_add_u32_e32 v187, v142, v130
	ds_read_b128 v[130:133], v186
	ds_read_b128 v[134:137], v186 offset:2048
	ds_read_b128 v[142:145], v141
	ds_read_b128 v[146:149], v141 offset:2048
	ds_read_b128 v[150:153], v141 offset:4096
	ds_read_b128 v[154:157], v141 offset:6144
	ds_read_b128 v[158:161], v0
	ds_read_b128 v[162:165], v0 offset:2048
	ds_read_b128 v[170:173], v187
	ds_read_b128 v[174:177], v187 offset:2048
	ds_read_b128 v[178:181], v187 offset:4096
	ds_read_b128 v[182:185], v187 offset:6144
	s_waitcnt lgkmcnt(0)
	v_lshlrev_b32_e32 v0, 1, v138
	v_and_b32_e32 v0, 0x80, v0
	v_mfma_f32_32x32x16_bf16 v[50:65], v[130:133], v[150:153], v[50:65]
	v_and_b32_e32 v141, 0xfffff9f, v138
	v_lshl_or_b32 v0, v140, 3, v0
	v_mad_u64_u32 v[140:141], s[16:17], v141, s3, v[0:1]
	s_waitcnt vmcnt(0) lgkmcnt(0)
	s_barrier
	v_mfma_f32_32x32x16_bf16 v[34:49], v[134:137], v[150:153], v[34:49]
	v_mfma_f32_32x32x16_bf16 v[82:97], v[130:133], v[146:149], v[82:97]
	v_mfma_f32_32x32x16_bf16 v[66:81], v[134:137], v[146:149], v[66:81]
	v_mfma_f32_32x32x16_bf16 v[2:17], v[134:137], v[154:157], v[2:17]
	v_mfma_f32_32x32x16_bf16 v[114:129], v[130:133], v[142:145], v[114:129]
	v_mfma_f32_32x32x16_bf16 v[98:113], v[134:137], v[142:145], v[98:113]
	v_mfma_f32_32x32x16_bf16 v[18:33], v[130:133], v[154:157], v[18:33]
	v_mfma_f32_32x32x16_bf16 v[50:65], v[158:161], v[178:181], v[50:65]
	v_mfma_f32_32x32x16_bf16 v[34:49], v[162:165], v[178:181], v[34:49]
	s_nop 10
	v_cvt_pk_bf16_f32 v50, v50, v51
	v_cvt_pk_bf16_f32 v51, v52, v53
	v_cvt_pk_bf16_f32 v52, v54, v55
	v_add_u32_e32 v54, 0x4000, v140
	v_cvt_pk_bf16_f32 v53, v56, v57
	ds_write2_b64 v54, v[50:51], v[52:53] offset0:128 offset1:130
	v_cvt_pk_bf16_f32 v50, v58, v59
	v_mfma_f32_32x32x16_bf16 v[82:97], v[158:161], v[174:177], v[82:97]
	v_cvt_pk_bf16_f32 v34, v34, v35
	v_cvt_pk_bf16_f32 v35, v36, v37
	v_cvt_pk_bf16_f32 v36, v38, v39
	v_cvt_pk_bf16_f32 v37, v40, v41
	ds_write2_b64 v54, v[34:35], v[36:37] offset0:136 offset1:138
	v_cvt_pk_bf16_f32 v34, v42, v43
	v_cvt_pk_bf16_f32 v35, v44, v45
	v_mfma_f32_32x32x16_bf16 v[66:81], v[162:165], v[174:177], v[66:81]
	v_cvt_pk_bf16_f32 v36, v46, v47
	v_cvt_pk_bf16_f32 v37, v48, v49
	ds_write2_b64 v54, v[34:35], v[36:37] offset0:140 offset1:142
	v_or_b32_e32 v34, 0x60, v138
	v_mad_u64_u32 v[34:35], s[16:17], v34, s3, v[0:1]
	v_cvt_pk_bf16_f32 v82, v82, v83
	v_mfma_f32_32x32x16_bf16 v[2:17], v[162:165], v[182:185], v[2:17]
	v_cvt_pk_bf16_f32 v83, v84, v85
	v_cvt_pk_bf16_f32 v84, v86, v87
	v_add_u32_e32 v86, 0x2000, v140
	s_nop 1
	v_cvt_pk_bf16_f32 v66, v66, v67
	v_cvt_pk_bf16_f32 v67, v68, v69
	v_cvt_pk_bf16_f32 v68, v70, v71
	v_cvt_pk_bf16_f32 v69, v72, v73
	v_mfma_f32_32x32x16_bf16 v[114:129], v[158:161], v[170:173], v[114:129]
	s_nop 1
	v_cvt_pk_bf16_f32 v2, v2, v3
	v_cvt_pk_bf16_f32 v3, v4, v5
	v_cvt_pk_bf16_f32 v4, v6, v7
	v_cvt_pk_bf16_f32 v5, v8, v9
	s_add_u32 s16, s92, s15
	v_cvt_pk_bf16_f32 v85, v88, v89
	ds_write2_b64 v86, v[66:67], v[68:69] offset0:72 offset1:74
	v_mfma_f32_32x32x16_bf16 v[98:113], v[162:165], v[170:173], v[98:113]
	s_nop 1
	v_cvt_pk_bf16_f32 v114, v114, v115
	v_cvt_pk_bf16_f32 v115, v116, v117
	v_cvt_pk_bf16_f32 v116, v118, v119
	v_cvt_pk_bf16_f32 v117, v120, v121
	v_cvt_pk_bf16_f32 v66, v74, v75
	v_cvt_pk_bf16_f32 v67, v76, v77
	v_cvt_pk_bf16_f32 v68, v78, v79
	v_mfma_f32_32x32x16_bf16 v[18:33], v[158:161], v[182:185], v[18:33]
	s_nop 1
	v_cvt_pk_bf16_f32 v98, v98, v99
	v_cvt_pk_bf16_f32 v99, v100, v101
	v_cvt_pk_bf16_f32 v100, v102, v103
	v_cvt_pk_bf16_f32 v101, v104, v105
	v_cvt_pk_bf16_f32 v69, v80, v81
	ds_write2_b64 v34, v[2:3], v[4:5] offset0:8 offset1:10
	v_cvt_pk_bf16_f32 v2, v10, v11
	s_nop 2
	v_cvt_pk_bf16_f32 v18, v18, v19
	v_cvt_pk_bf16_f32 v19, v20, v21
	v_cvt_pk_bf16_f32 v20, v22, v23
	v_cvt_pk_bf16_f32 v21, v24, v25
	v_cvt_pk_bf16_f32 v3, v12, v13
	v_cvt_pk_bf16_f32 v4, v14, v15
	v_cvt_pk_bf16_f32 v5, v16, v17
	v_and_b32_e32 v0, 0xf0, v139
	s_addc_u32 s17, s93, 0
	ds_write2_b64 v140, v[114:115], v[116:117] offset1:2
	v_cvt_pk_bf16_f32 v114, v122, v123
	v_cvt_pk_bf16_f32 v115, v124, v125
	v_cvt_pk_bf16_f32 v116, v126, v127
	v_cvt_pk_bf16_f32 v117, v128, v129
	ds_write2_b64 v140, v[98:99], v[100:101] offset0:8 offset1:10
	v_cvt_pk_bf16_f32 v98, v106, v107
	v_cvt_pk_bf16_f32 v99, v108, v109
	v_cvt_pk_bf16_f32 v100, v110, v111
	v_cvt_pk_bf16_f32 v101, v112, v113
	ds_write2_b64 v86, v[82:83], v[84:85] offset0:64 offset1:66
	v_cvt_pk_bf16_f32 v82, v90, v91
	v_cvt_pk_bf16_f32 v83, v92, v93
	v_cvt_pk_bf16_f32 v84, v94, v95
	v_cvt_pk_bf16_f32 v85, v96, v97
	ds_write2_b64 v86, v[66:67], v[68:69] offset0:76 offset1:78
	v_cvt_pk_bf16_f32 v51, v60, v61
	v_cvt_pk_bf16_f32 v52, v62, v63
	v_cvt_pk_bf16_f32 v53, v64, v65
	ds_write2_b64 v34, v[18:19], v[20:21] offset1:2
	v_cvt_pk_bf16_f32 v18, v26, v27
	v_cvt_pk_bf16_f32 v19, v28, v29
	v_cvt_pk_bf16_f32 v20, v30, v31
	v_cvt_pk_bf16_f32 v21, v32, v33
	ds_write2_b64 v34, v[2:3], v[4:5] offset0:12 offset1:14
	v_lshl_add_u64 v[2:3], s[16:17], 0, v[0:1]
	s_mov_b32 s15, 0
	ds_write2_b64 v140, v[114:115], v[116:117] offset0:4 offset1:6
	ds_write2_b64 v140, v[98:99], v[100:101] offset0:12 offset1:14
	ds_write2_b64 v86, v[82:83], v[84:85] offset0:68 offset1:70
	ds_write2_b64 v54, v[50:51], v[52:53] offset0:132 offset1:134
	ds_write2_b64 v34, v[18:19], v[20:21] offset0:4 offset1:6
	s_waitcnt lgkmcnt(0)
	s_barrier

.LBB0_1322:
	s_mul_i32 s16, s13, 0x6000
	v_add_u32_e32 v146, s16, v144
	v_add_u32_e32 v147, s16, v142
	v_add_u32_e32 v198, v146, v131
	v_add_u32_e32 v199, v147, v131
	v_add_u32_e32 v200, v146, v141
	v_add_u32_e32 v201, v147, v141
	s_waitcnt vmcnt(6)
	s_barrier
	ds_read_b128 v[146:149], v198
	ds_read_b128 v[150:153], v198 offset:2048
	ds_read_b128 v[154:157], v199
	ds_read_b128 v[158:161], v199 offset:2048
	ds_read_b128 v[162:165], v199 offset:4096
	ds_read_b128 v[170:173], v199 offset:6144
	ds_read_b128 v[174:177], v200
	ds_read_b128 v[178:181], v200 offset:2048
	ds_read_b128 v[182:185], v201
	ds_read_b128 v[186:189], v201 offset:2048
	ds_read_b128 v[190:193], v201 offset:4096
	ds_read_b128 v[194:197], v201 offset:6144
	s_waitcnt lgkmcnt(0)
	v_mfma_f32_32x32x16_bf16 v[114:129], v[146:149], v[154:157], v[114:129]
	s_waitcnt vmcnt(0)
	s_barrier
	v_mfma_f32_32x32x16_bf16 v[82:97], v[146:149], v[158:161], v[82:97]
	v_mfma_f32_32x32x16_bf16 v[50:65], v[146:149], v[162:165], v[50:65]
	v_mfma_f32_32x32x16_bf16 v[18:33], v[146:149], v[170:173], v[18:33]
	s_add_i32 s14, s16, 0xffffa000
	s_cmp_gt_i32 s13, 0
	s_cselect_b32 s14, s14, 0xc000
	v_add_u32_e32 v148, s14, v145
	v_lshl_add_u64 v[138:139], v[134:135], 0, v[0:1]
	v_readfirstlane_b32 s14, v148
	v_add_u32_e32 v146, 0x1000, v148
	v_lshl_add_u64 v[136:137], v[138:139], 0, s[18:19]
	s_mov_b32 m0, s14
	v_readfirstlane_b32 s14, v146
	v_add_u32_e32 v146, 0x2000, v148
	global_load_lds_dwordx4 v[136:137], off
	v_mfma_f32_32x32x16_bf16 v[98:113], v[150:153], v[154:157], v[98:113]
	v_lshl_add_u64 v[136:137], v[138:139], 0, s[20:21]
	s_mov_b32 m0, s14
	v_readfirstlane_b32 s14, v146
	v_add_u32_e32 v146, 0x3000, v148
	global_load_lds_dwordx4 v[136:137], off
	v_mfma_f32_32x32x16_bf16 v[66:81], v[150:153], v[158:161], v[66:81]
	v_lshl_add_u64 v[136:137], v[138:139], 0, s[40:41]
	s_mov_b32 m0, s14
	v_readfirstlane_b32 s14, v146
	global_load_lds_dwordx4 v[136:137], off
	v_mfma_f32_32x32x16_bf16 v[34:49], v[150:153], v[162:165], v[34:49]
	v_lshl_add_u64 v[136:137], v[138:139], 0, s[42:43]
	s_mov_b32 m0, s14
	s_mov_b64 s[14:15], 0x720000
	global_load_lds_dwordx4 v[136:137], off
	v_mfma_f32_32x32x16_bf16 v[2:17], v[150:153], v[170:173], v[2:17]
	v_lshl_add_u64 v[136:137], v[132:133], 0, v[0:1]
	v_add_u32_e32 v149, 0x4000, v148
	v_lshl_add_u64 v[146:147], v[136:137], 0, s[14:15]
	v_readfirstlane_b32 s14, v149
	s_mov_b32 m0, s14
	s_mov_b64 s[14:15], 0x721000
	v_add_u32_e32 v148, 0x5000, v148
	global_load_lds_dwordx4 v[146:147], off
	v_mfma_f32_32x32x16_bf16 v[114:129], v[174:177], v[182:185], v[114:129]
	v_lshl_add_u64 v[146:147], v[136:137], 0, s[14:15]
	v_readfirstlane_b32 s14, v148
	s_mov_b32 m0, s14
	s_add_i32 s14, s13, 1
	s_cmp_lg_u32 s13, 2
	s_cselect_b32 s13, s14, 0
	s_mul_i32 s14, s13, 0x6000
	s_add_i32 s15, s14, 0xffffa000
	global_load_lds_dwordx4 v[146:147], off
	v_mfma_f32_32x32x16_bf16 v[98:113], v[178:181], v[182:185], v[98:113]
	s_cmp_gt_i32 s13, 0
	s_cselect_b32 s15, s15, 0xc000
	s_mov_b64 s[16:17], 0x730000
	v_lshl_add_u64 v[132:133], v[132:133], 0, s[58:59]
	v_lshl_add_u64 v[134:135], v[134:135], 0, s[96:97]
	v_add_u32_e32 v148, s15, v145
	v_add_u32_e32 v149, 0x1000, v148
	v_readfirstlane_b32 s15, v148
	v_lshl_add_u64 v[146:147], v[138:139], 0, s[46:47]
	s_mov_b32 m0, s15
	v_readfirstlane_b32 s15, v149
	v_add_u32_e32 v149, 0x2000, v148
	global_load_lds_dwordx4 v[146:147], off
	v_mfma_f32_32x32x16_bf16 v[82:97], v[174:177], v[186:189], v[82:97]
	v_lshl_add_u64 v[146:147], v[138:139], 0, s[48:49]
	s_mov_b32 m0, s15
	v_readfirstlane_b32 s15, v149
	global_load_lds_dwordx4 v[146:147], off
	v_mfma_f32_32x32x16_bf16 v[66:81], v[178:181], v[186:189], v[66:81]
	v_lshl_add_u64 v[146:147], v[138:139], 0, s[50:51]
	s_mov_b32 m0, s15
	v_lshl_add_u64 v[138:139], v[138:139], 0, s[56:57]
	global_load_lds_dwordx4 v[146:147], off
	v_mfma_f32_32x32x16_bf16 v[50:65], v[174:177], v[190:193], v[50:65]
	v_add_u32_e32 v146, 0x3000, v148
	s_nop 0
	v_readfirstlane_b32 s15, v146
	v_add_u32_e32 v146, 0x4000, v148
	s_mov_b32 m0, s15
	v_readfirstlane_b32 s15, v146
	global_load_lds_dwordx4 v[138:139], off
	v_mfma_f32_32x32x16_bf16 v[34:49], v[178:181], v[190:193], v[34:49]
	v_lshl_add_u64 v[138:139], v[136:137], 0, s[16:17]
	s_mov_b32 m0, s15
	s_mov_b64 s[16:17], 0x731000
	global_load_lds_dwordx4 v[138:139], off
	v_mfma_f32_32x32x16_bf16 v[18:33], v[174:177], v[194:197], v[18:33]
	v_add_u32_e32 v138, 0x5000, v148
	v_lshl_add_u64 v[136:137], v[136:137], 0, s[16:17]
	v_readfirstlane_b32 s15, v138
	s_mov_b32 m0, s15
	s_nop 0
	global_load_lds_dwordx4 v[136:137], off
	v_mfma_f32_32x32x16_bf16 v[2:17], v[178:181], v[194:197], v[2:17]
	v_add_u32_e32 v136, s14, v144
	v_add_u32_e32 v137, s14, v142
	s_add_i32 s14, s13, 1
	s_cmp_lg_u32 s13, 2
	s_cselect_b32 s13, s14, 0
	s_add_i32 s12, s12, -2
	s_cmp_eq_u32 s12, 0
	v_add_u32_e32 v194, v136, v131
	v_add_u32_e32 v195, v137, v131
	v_add_u32_e32 v196, v136, v141
	v_add_u32_e32 v197, v137, v141
	ds_read_b128 v[136:139], v194
	ds_read_b128 v[146:149], v194 offset:2048
	ds_read_b128 v[150:153], v195
	ds_read_b128 v[154:157], v195 offset:2048
	ds_read_b128 v[158:161], v195 offset:4096
	ds_read_b128 v[162:165], v195 offset:6144
	ds_read_b128 v[170:173], v196
	ds_read_b128 v[174:177], v196 offset:2048
	ds_read_b128 v[178:181], v197
	ds_read_b128 v[182:185], v197 offset:2048
	ds_read_b128 v[186:189], v197 offset:4096
	ds_read_b128 v[190:193], v197 offset:6144
	s_waitcnt lgkmcnt(0)
	s_nop 0
	v_mfma_f32_32x32x16_bf16 v[114:129], v[136:139], v[150:153], v[114:129]
	v_mfma_f32_32x32x16_bf16 v[98:113], v[146:149], v[150:153], v[98:113]
	v_mfma_f32_32x32x16_bf16 v[82:97], v[136:139], v[154:157], v[82:97]
	v_mfma_f32_32x32x16_bf16 v[66:81], v[146:149], v[154:157], v[66:81]
	v_mfma_f32_32x32x16_bf16 v[50:65], v[136:139], v[158:161], v[50:65]
	v_mfma_f32_32x32x16_bf16 v[34:49], v[146:149], v[158:161], v[34:49]
	v_mfma_f32_32x32x16_bf16 v[18:33], v[136:139], v[162:165], v[18:33]
	v_mfma_f32_32x32x16_bf16 v[2:17], v[146:149], v[162:165], v[2:17]
	v_mfma_f32_32x32x16_bf16 v[114:129], v[170:173], v[178:181], v[114:129]
	v_mfma_f32_32x32x16_bf16 v[98:113], v[174:177], v[178:181], v[98:113]
	v_mfma_f32_32x32x16_bf16 v[82:97], v[170:173], v[182:185], v[82:97]
	v_mfma_f32_32x32x16_bf16 v[66:81], v[174:177], v[182:185], v[66:81]
	v_mfma_f32_32x32x16_bf16 v[50:65], v[170:173], v[186:189], v[50:65]
	v_mfma_f32_32x32x16_bf16 v[34:49], v[174:177], v[186:189], v[34:49]
	v_mfma_f32_32x32x16_bf16 v[18:33], v[170:173], v[190:193], v[18:33]
	v_mfma_f32_32x32x16_bf16 v[2:17], v[174:177], v[190:193], v[2:17]
	s_cbranch_scc0 .LBB0_1322
	s_waitcnt vmcnt(6)
	s_barrier
	v_add_u32_e32 v0, v144, v131
	v_add_u32_e32 v164, v142, v131
	v_add_u32_e32 v165, v144, v141
	v_add_u32_e32 v190, v142, v141
	ds_read_b128 v[132:135], v0
	ds_read_b128 v[136:139], v0 offset:2048
	ds_read_b128 v[144:147], v164
	ds_read_b128 v[148:151], v164 offset:2048
	ds_read_b128 v[152:155], v164 offset:4096
	ds_read_b128 v[156:159], v164 offset:6144
	ds_read_b128 v[160:163], v165
	ds_read_b128 v[170:173], v165 offset:2048
	ds_read_b128 v[174:177], v190
	ds_read_b128 v[178:181], v190 offset:2048
	ds_read_b128 v[182:185], v190 offset:4096
	ds_read_b128 v[186:189], v190 offset:6144
	s_waitcnt lgkmcnt(0)
	v_or_b32_e32 v0, 0xa000, v143
	v_mfma_f32_32x32x16_bf16 v[114:129], v[132:135], v[144:147], v[114:129]
	s_waitcnt vmcnt(0)
	s_barrier
	s_movk_i32 s12, 0x80
	v_cmp_gt_u32_e64 s[48:49], s12, v130
	v_mfma_f32_32x32x16_bf16 v[98:113], v[136:139], v[144:147], v[98:113]
	v_mfma_f32_32x32x16_bf16 v[82:97], v[132:135], v[148:151], v[82:97]
	v_mfma_f32_32x32x16_bf16 v[66:81], v[136:139], v[148:151], v[66:81]
	v_mfma_f32_32x32x16_bf16 v[50:65], v[132:135], v[152:155], v[50:65]
	v_mfma_f32_32x32x16_bf16 v[34:49], v[136:139], v[152:155], v[34:49]
	v_mfma_f32_32x32x16_bf16 v[18:33], v[132:135], v[156:159], v[18:33]
	v_add_u32_e32 v132, 0x6000, v142
	v_mfma_f32_32x32x16_bf16 v[2:17], v[136:139], v[156:159], v[2:17]
	v_mfma_f32_32x32x16_bf16 v[114:129], v[160:163], v[174:177], v[114:129]
	v_mfma_f32_32x32x16_bf16 v[98:113], v[170:173], v[174:177], v[98:113]
	v_mfma_f32_32x32x16_bf16 v[82:97], v[160:163], v[178:181], v[82:97]
	v_mfma_f32_32x32x16_bf16 v[66:81], v[170:173], v[178:181], v[66:81]
	v_mfma_f32_32x32x16_bf16 v[50:65], v[160:163], v[182:185], v[50:65]
	v_mfma_f32_32x32x16_bf16 v[34:49], v[170:173], v[182:185], v[34:49]
	v_mfma_f32_32x32x16_bf16 v[18:33], v[160:163], v[186:189], v[18:33]
	v_mfma_f32_32x32x16_bf16 v[2:17], v[170:173], v[186:189], v[2:17]
	v_add_u32_e32 v186, v0, v131
	v_add_u32_e32 v131, v132, v131
	v_add_u32_e32 v0, v0, v141
	v_add_u32_e32 v141, v132, v141
	ds_read_b128 v[132:135], v186
	ds_read_b128 v[136:139], v186 offset:2048
	ds_read_b128 v[142:145], v131
	ds_read_b128 v[146:149], v131 offset:2048
	ds_read_b128 v[150:153], v131 offset:4096
	ds_read_b128 v[154:157], v131 offset:6144
	ds_read_b128 v[158:161], v0
	ds_read_b128 v[162:165], v0 offset:2048
	ds_read_b128 v[170:173], v141
	ds_read_b128 v[174:177], v141 offset:2048
	ds_read_b128 v[178:181], v141 offset:4096
	ds_read_b128 v[182:185], v141 offset:6144
	s_waitcnt lgkmcnt(0)
	s_waitcnt vmcnt(0) lgkmcnt(0)
	s_barrier
	v_mfma_f32_32x32x16_bf16 v[114:129], v[132:135], v[142:145], v[114:129]
	v_mfma_f32_32x32x16_bf16 v[98:113], v[136:139], v[142:145], v[98:113]
	v_and_b32_e32 v143, 64, v130
	v_and_b32_e32 v144, 31, v130
	v_mfma_f32_32x32x16_bf16 v[82:97], v[132:135], v[146:149], v[82:97]
	v_mfma_f32_32x32x16_bf16 v[66:81], v[136:139], v[146:149], v[66:81]
	v_mfma_f32_32x32x16_bf16 v[50:65], v[132:135], v[150:153], v[50:65]
	v_mfma_f32_32x32x16_bf16 v[34:49], v[136:139], v[150:153], v[34:49]
	v_mfma_f32_32x32x16_bf16 v[18:33], v[132:135], v[154:157], v[18:33]
	v_mfma_f32_32x32x16_bf16 v[2:17], v[136:139], v[154:157], v[2:17]
	v_mfma_f32_32x32x16_bf16 v[114:129], v[158:161], v[170:173], v[114:129]
	v_mfma_f32_32x32x16_bf16 v[98:113], v[162:165], v[170:173], v[98:113]
	v_mfma_f32_32x32x16_bf16 v[82:97], v[158:161], v[174:177], v[82:97]
	v_mfma_f32_32x32x16_bf16 v[66:81], v[162:165], v[174:177], v[66:81]
	v_mfma_f32_32x32x16_bf16 v[50:65], v[158:161], v[178:181], v[50:65]
	v_mfma_f32_32x32x16_bf16 v[34:49], v[162:165], v[178:181], v[34:49]
	v_mfma_f32_32x32x16_bf16 v[18:33], v[158:161], v[182:185], v[18:33]
	v_mfma_f32_32x32x16_bf16 v[2:17], v[162:165], v[182:185], v[2:17]
	s_and_saveexec_b64 s[12:13], s[48:49]
	s_cbranch_execz .LBB0_1325
	v_mul_u32_u24_e32 v0, 0x210, v144
	v_lshlrev_b32_e32 v131, 4, v140
	v_lshlrev_b32_e32 v132, 2, v143
	v_add3_u32 v0, v0, v131, v132
	ds_write_b128 v0, v[114:117]
	ds_write_b128 v0, v[118:121] offset:32
	ds_write_b128 v0, v[122:125] offset:64
	ds_write_b128 v0, v[126:129] offset:96
	ds_write_b128 v0, v[98:101] offset:128
	ds_write_b128 v0, v[102:105] offset:160
	ds_write_b128 v0, v[106:109] offset:192
	ds_write_b128 v0, v[110:113] offset:224
	ds_write_b128 v0, v[82:85] offset:16896
	ds_write_b128 v0, v[86:89] offset:16928
	ds_write_b128 v0, v[90:93] offset:16960
	ds_write_b128 v0, v[94:97] offset:16992
	ds_write_b128 v0, v[66:69] offset:17024
	ds_write_b128 v0, v[70:73] offset:17056
	ds_write_b128 v0, v[74:77] offset:17088
	ds_write_b128 v0, v[78:81] offset:17120
	ds_write_b128 v0, v[50:53] offset:33792
	ds_write_b128 v0, v[54:57] offset:33824
	ds_write_b128 v0, v[58:61] offset:33856
	ds_write_b128 v0, v[62:65] offset:33888
	ds_write_b128 v0, v[34:37] offset:33920
	ds_write_b128 v0, v[38:41] offset:33952
	ds_write_b128 v0, v[42:45] offset:33984
	ds_write_b128 v0, v[46:49] offset:34016
	v_or_b32_e32 v0, 0x60, v130
	v_mul_lo_u32 v0, v0, s94
	v_add3_u32 v0, v0, v131, v132
	ds_write_b128 v0, v[18:21]
	ds_write_b128 v0, v[22:25] offset:32
	ds_write_b128 v0, v[26:29] offset:64
	ds_write_b128 v0, v[30:33] offset:96
	ds_write_b128 v0, v[2:5] offset:128
	ds_write_b128 v0, v[6:9] offset:160
	ds_write_b128 v0, v[10:13] offset:192
	ds_write_b128 v0, v[14:17] offset:224

.LBB0_1421:
	s_mul_i32 s21, s20, 0x6000
	v_add_u32_e32 v146, s21, v145
	v_add_u32_e32 v147, s21, v143
	v_add_u32_e32 v198, v146, v141
	v_add_u32_e32 v199, v147, v141
	v_add_u32_e32 v200, v146, v142
	v_add_u32_e32 v201, v147, v142
	s_waitcnt vmcnt(6)
	s_barrier
	ds_read_b128 v[146:149], v198
	ds_read_b128 v[150:153], v198 offset:2048
	ds_read_b128 v[154:157], v199
	ds_read_b128 v[158:161], v199 offset:2048
	ds_read_b128 v[162:165], v199 offset:4096
	ds_read_b128 v[170:173], v199 offset:6144
	ds_read_b128 v[174:177], v200
	ds_read_b128 v[178:181], v200 offset:2048
	ds_read_b128 v[182:185], v201
	ds_read_b128 v[186:189], v201 offset:2048
	ds_read_b128 v[190:193], v201 offset:4096
	ds_read_b128 v[194:197], v201 offset:6144
	s_waitcnt lgkmcnt(0)
	v_mfma_f32_32x32x16_bf16 v[114:129], v[146:149], v[154:157], v[114:129]
	s_waitcnt vmcnt(0)
	s_barrier
	v_mfma_f32_32x32x16_bf16 v[82:97], v[146:149], v[158:161], v[82:97]
	v_mfma_f32_32x32x16_bf16 v[50:65], v[146:149], v[162:165], v[50:65]
	v_mfma_f32_32x32x16_bf16 v[18:33], v[146:149], v[170:173], v[18:33]
	s_add_i32 s22, s21, 0xffffa000
	s_cmp_gt_i32 s20, 0
	s_cselect_b32 s22, s22, 0xc000
	v_add_u32_e32 v148, s22, v139
	v_lshl_add_u64 v[136:137], v[132:133], 0, v[0:1]
	v_readfirstlane_b32 s22, v148
	v_add_u32_e32 v146, 0x1000, v148
	v_lshl_add_u64 v[134:135], v[136:137], 0, s[34:35]
	s_mov_b32 m0, s22
	v_readfirstlane_b32 s22, v146
	v_add_u32_e32 v146, 0x2000, v148
	global_load_lds_dwordx4 v[134:135], off
	v_mfma_f32_32x32x16_bf16 v[98:113], v[150:153], v[154:157], v[98:113]
	v_lshl_add_u64 v[134:135], v[136:137], 0, s[36:37]
	s_mov_b32 m0, s22
	v_readfirstlane_b32 s22, v146
	v_add_u32_e32 v146, 0x3000, v148
	global_load_lds_dwordx4 v[134:135], off
	v_mfma_f32_32x32x16_bf16 v[66:81], v[150:153], v[158:161], v[66:81]
	v_lshl_add_u64 v[134:135], v[136:137], 0, s[24:25]
	s_mov_b32 m0, s22
	v_readfirstlane_b32 s22, v146
	global_load_lds_dwordx4 v[134:135], off
	v_mfma_f32_32x32x16_bf16 v[34:49], v[150:153], v[162:165], v[34:49]
	v_lshl_add_u64 v[134:135], v[136:137], 0, s[38:39]
	s_mov_b32 m0, s22
	s_mov_b64 s[22:23], 0x920000
	global_load_lds_dwordx4 v[134:135], off
	v_mfma_f32_32x32x16_bf16 v[2:17], v[150:153], v[170:173], v[2:17]
	v_lshl_add_u64 v[134:135], v[130:131], 0, v[0:1]
	v_add_u32_e32 v149, 0x4000, v148
	v_lshl_add_u64 v[146:147], v[134:135], 0, s[22:23]
	v_readfirstlane_b32 s22, v149
	s_mov_b32 m0, s22
	s_mov_b64 s[22:23], 0x921000
	v_add_u32_e32 v148, 0x5000, v148
	global_load_lds_dwordx4 v[146:147], off
	v_mfma_f32_32x32x16_bf16 v[114:129], v[174:177], v[182:185], v[114:129]
	v_lshl_add_u64 v[146:147], v[134:135], 0, s[22:23]
	v_readfirstlane_b32 s22, v148
	s_mov_b32 m0, s22
	v_lshl_add_u64 v[130:131], v[130:131], 0, s[58:59]
	global_load_lds_dwordx4 v[146:147], off
	v_mfma_f32_32x32x16_bf16 v[98:113], v[178:181], v[182:185], v[98:113]
	s_add_i32 s21, s20, 1
	s_cmp_lg_u32 s20, 2
	s_cselect_b32 s20, s21, 0
	s_mul_i32 s21, s20, 0x6000
	s_add_i32 s22, s21, 0xffffa000
	s_cmp_gt_i32 s20, 0
	s_cselect_b32 s22, s22, 0xc000
	v_lshl_add_u64 v[132:133], v[132:133], 0, s[96:97]
	v_add_u32_e32 v148, s22, v139
	v_add_u32_e32 v149, 0x1000, v148
	v_readfirstlane_b32 s22, v148
	v_lshl_add_u64 v[146:147], v[136:137], 0, s[88:89]
	s_mov_b32 m0, s22
	v_readfirstlane_b32 s22, v149
	v_add_u32_e32 v149, 0x2000, v148
	global_load_lds_dwordx4 v[146:147], off
	v_mfma_f32_32x32x16_bf16 v[82:97], v[174:177], v[186:189], v[82:97]
	v_lshl_add_u64 v[146:147], v[136:137], 0, s[4:5]
	s_mov_b32 m0, s22
	v_readfirstlane_b32 s22, v149
	global_load_lds_dwordx4 v[146:147], off
	v_mfma_f32_32x32x16_bf16 v[66:81], v[178:181], v[186:189], v[66:81]
	v_lshl_add_u64 v[146:147], v[136:137], 0, s[84:85]
	s_mov_b32 m0, s22
	v_lshl_add_u64 v[136:137], v[136:137], 0, s[86:87]
	global_load_lds_dwordx4 v[146:147], off
	v_mfma_f32_32x32x16_bf16 v[50:65], v[174:177], v[190:193], v[50:65]
	v_add_u32_e32 v146, 0x3000, v148
	s_nop 0
	v_readfirstlane_b32 s22, v146
	s_mov_b32 m0, s22
	s_mov_b64 s[22:23], 0x930000
	v_add_u32_e32 v146, 0x4000, v148
	global_load_lds_dwordx4 v[136:137], off
	v_mfma_f32_32x32x16_bf16 v[34:49], v[178:181], v[190:193], v[34:49]
	v_lshl_add_u64 v[136:137], v[134:135], 0, s[22:23]
	v_readfirstlane_b32 s22, v146
	s_mov_b32 m0, s22
	s_mov_b64 s[22:23], 0x931000
	global_load_lds_dwordx4 v[136:137], off
	v_mfma_f32_32x32x16_bf16 v[18:33], v[174:177], v[194:197], v[18:33]
	v_add_u32_e32 v136, 0x5000, v148
	v_lshl_add_u64 v[134:135], v[134:135], 0, s[22:23]
	v_readfirstlane_b32 s22, v136
	s_mov_b32 m0, s22
	s_nop 0
	global_load_lds_dwordx4 v[134:135], off
	v_mfma_f32_32x32x16_bf16 v[2:17], v[178:181], v[194:197], v[2:17]
	v_add_u32_e32 v134, s21, v145
	v_add_u32_e32 v135, s21, v143
	s_add_i32 s21, s20, 1
	s_cmp_lg_u32 s20, 2
	s_cselect_b32 s20, s21, 0
	s_add_i32 s19, s19, -2
	s_cmp_eq_u32 s19, 0
	v_add_u32_e32 v194, v134, v141
	v_add_u32_e32 v195, v135, v141
	v_add_u32_e32 v196, v134, v142
	v_add_u32_e32 v197, v135, v142
	ds_read_b128 v[134:137], v194
	ds_read_b128 v[146:149], v194 offset:2048
	ds_read_b128 v[150:153], v195
	ds_read_b128 v[154:157], v195 offset:2048
	ds_read_b128 v[158:161], v195 offset:4096
	ds_read_b128 v[162:165], v195 offset:6144
	ds_read_b128 v[170:173], v196
	ds_read_b128 v[174:177], v196 offset:2048
	ds_read_b128 v[178:181], v197
	ds_read_b128 v[182:185], v197 offset:2048
	ds_read_b128 v[186:189], v197 offset:4096
	ds_read_b128 v[190:193], v197 offset:6144
	s_waitcnt lgkmcnt(0)
	s_nop 0
	v_mfma_f32_32x32x16_bf16 v[114:129], v[134:137], v[150:153], v[114:129]
	v_mfma_f32_32x32x16_bf16 v[98:113], v[146:149], v[150:153], v[98:113]
	v_mfma_f32_32x32x16_bf16 v[82:97], v[134:137], v[154:157], v[82:97]
	v_mfma_f32_32x32x16_bf16 v[66:81], v[146:149], v[154:157], v[66:81]
	v_mfma_f32_32x32x16_bf16 v[50:65], v[134:137], v[158:161], v[50:65]
	v_mfma_f32_32x32x16_bf16 v[34:49], v[146:149], v[158:161], v[34:49]
	v_mfma_f32_32x32x16_bf16 v[18:33], v[134:137], v[162:165], v[18:33]
	v_mfma_f32_32x32x16_bf16 v[2:17], v[146:149], v[162:165], v[2:17]
	v_mfma_f32_32x32x16_bf16 v[114:129], v[170:173], v[178:181], v[114:129]
	v_mfma_f32_32x32x16_bf16 v[98:113], v[174:177], v[178:181], v[98:113]
	v_mfma_f32_32x32x16_bf16 v[82:97], v[170:173], v[182:185], v[82:97]
	v_mfma_f32_32x32x16_bf16 v[66:81], v[174:177], v[182:185], v[66:81]
	v_mfma_f32_32x32x16_bf16 v[50:65], v[170:173], v[186:189], v[50:65]
	v_mfma_f32_32x32x16_bf16 v[34:49], v[174:177], v[186:189], v[34:49]
	v_mfma_f32_32x32x16_bf16 v[18:33], v[170:173], v[190:193], v[18:33]
	v_mfma_f32_32x32x16_bf16 v[2:17], v[174:177], v[190:193], v[2:17]
	s_cbranch_scc0 .LBB0_1421
	s_waitcnt vmcnt(6)
	s_barrier
	v_add_u32_e32 v0, v145, v141
	v_add_u32_e32 v190, v143, v141
	v_add_u32_e32 v145, v145, v142
	v_add_u32_e32 v191, v143, v142
	ds_read_b128 v[130:133], v0
	ds_read_b128 v[134:137], v0 offset:2048
	ds_read_b128 v[146:149], v190
	ds_read_b128 v[150:153], v190 offset:2048
	ds_read_b128 v[154:157], v190 offset:4096
	ds_read_b128 v[158:161], v190 offset:6144
	ds_read_b128 v[162:165], v145
	ds_read_b128 v[170:173], v145 offset:2048
	ds_read_b128 v[174:177], v191
	ds_read_b128 v[178:181], v191 offset:2048
	ds_read_b128 v[182:185], v191 offset:4096
	ds_read_b128 v[186:189], v191 offset:6144
	s_waitcnt lgkmcnt(0)
	v_or_b32_e32 v0, 0xa000, v144
	v_mfma_f32_32x32x16_bf16 v[50:65], v[130:133], v[154:157], v[50:65]
	s_waitcnt vmcnt(0)
	s_barrier
	v_add_u32_e32 v190, v141, v0
	v_add_u32_e32 v0, v142, v0
	s_lshl_b32 s19, s17, 9
	s_and_b32 s19, s19, 0xc00
	s_lshr_b32 s18, s18, 5
	v_mfma_f32_32x32x16_bf16 v[34:49], v[134:137], v[154:157], v[34:49]
	s_add_i32 s18, s18, s19
	s_lshl_b32 s19, s17, 3
	s_and_b32 s19, s19, 8
	v_mfma_f32_32x32x16_bf16 v[82:97], v[130:133], v[150:153], v[82:97]
	v_mfma_f32_32x32x16_bf16 v[66:81], v[134:137], v[150:153], v[66:81]
	v_mfma_f32_32x32x16_bf16 v[2:17], v[134:137], v[158:161], v[2:17]
	v_mfma_f32_32x32x16_bf16 v[114:129], v[130:133], v[146:149], v[114:129]
	v_mfma_f32_32x32x16_bf16 v[98:113], v[134:137], v[146:149], v[98:113]
	v_mfma_f32_32x32x16_bf16 v[18:33], v[130:133], v[158:161], v[18:33]
	v_add_u32_e32 v130, 0x6000, v143
	v_add_u32_e32 v141, v141, v130
	v_mfma_f32_32x32x16_bf16 v[50:65], v[162:165], v[182:185], v[50:65]
	v_mfma_f32_32x32x16_bf16 v[34:49], v[170:173], v[182:185], v[34:49]
	v_mfma_f32_32x32x16_bf16 v[82:97], v[162:165], v[178:181], v[82:97]
	v_mfma_f32_32x32x16_bf16 v[66:81], v[170:173], v[178:181], v[66:81]
	v_mfma_f32_32x32x16_bf16 v[2:17], v[170:173], v[186:189], v[2:17]
	v_mfma_f32_32x32x16_bf16 v[114:129], v[162:165], v[174:177], v[114:129]
	v_mfma_f32_32x32x16_bf16 v[98:113], v[170:173], v[174:177], v[98:113]
	v_mfma_f32_32x32x16_bf16 v[18:33], v[162:165], v[186:189], v[18:33]
	v_add_u32_e32 v186, v142, v130
	ds_read_b128 v[130:133], v190
	ds_read_b128 v[134:137], v190 offset:2048
	ds_read_b128 v[142:145], v141
	ds_read_b128 v[146:149], v141 offset:2048
	ds_read_b128 v[150:153], v141 offset:4096
	ds_read_b128 v[154:157], v141 offset:6144
	ds_read_b128 v[158:161], v0
	ds_read_b128 v[162:165], v0 offset:2048
	ds_read_b128 v[170:173], v186
	ds_read_b128 v[174:177], v186 offset:2048
	ds_read_b128 v[178:181], v186 offset:4096
	ds_read_b128 v[182:185], v186 offset:6144
	s_waitcnt lgkmcnt(0)
	v_lshlrev_b32_e32 v0, 1, v138
	v_and_b32_e32 v0, 0x80, v0
	v_and_b32_e32 v141, 0xfffff9f, v138
	v_lshl_or_b32 v0, v140, 3, v0
	v_mad_u64_u32 v[140:141], s[20:21], v141, s3, v[0:1]
	v_mfma_f32_32x32x16_bf16 v[50:65], v[130:133], v[150:153], v[50:65]
	s_waitcnt vmcnt(0) lgkmcnt(0)
	s_barrier
	v_mfma_f32_32x32x16_bf16 v[34:49], v[134:137], v[150:153], v[34:49]
	v_mfma_f32_32x32x16_bf16 v[82:97], v[130:133], v[146:149], v[82:97]
	v_mfma_f32_32x32x16_bf16 v[66:81], v[134:137], v[146:149], v[66:81]
	v_mfma_f32_32x32x16_bf16 v[2:17], v[134:137], v[154:157], v[2:17]
	v_mfma_f32_32x32x16_bf16 v[114:129], v[130:133], v[142:145], v[114:129]
	v_mfma_f32_32x32x16_bf16 v[98:113], v[134:137], v[142:145], v[98:113]
	v_mfma_f32_32x32x16_bf16 v[18:33], v[130:133], v[154:157], v[18:33]
	v_mfma_f32_32x32x16_bf16 v[50:65], v[158:161], v[178:181], v[50:65]
	v_mfma_f32_32x32x16_bf16 v[34:49], v[162:165], v[178:181], v[34:49]
	s_nop 10
	v_cvt_pk_bf16_f32 v50, v50, v51
	v_cvt_pk_bf16_f32 v51, v52, v53
	v_cvt_pk_bf16_f32 v52, v54, v55
	v_add_u32_e32 v54, 0x4000, v140
	v_cvt_pk_bf16_f32 v53, v56, v57
	ds_write2_b64 v54, v[50:51], v[52:53] offset0:128 offset1:130
	v_cvt_pk_bf16_f32 v50, v58, v59
	v_mfma_f32_32x32x16_bf16 v[82:97], v[158:161], v[174:177], v[82:97]
	v_cvt_pk_bf16_f32 v34, v34, v35
	v_cvt_pk_bf16_f32 v35, v36, v37
	v_cvt_pk_bf16_f32 v36, v38, v39
	v_cvt_pk_bf16_f32 v37, v40, v41
	ds_write2_b64 v54, v[34:35], v[36:37] offset0:136 offset1:138
	v_cvt_pk_bf16_f32 v34, v42, v43
	v_cvt_pk_bf16_f32 v35, v44, v45
	v_mfma_f32_32x32x16_bf16 v[66:81], v[162:165], v[174:177], v[66:81]
	v_cvt_pk_bf16_f32 v36, v46, v47
	v_cvt_pk_bf16_f32 v37, v48, v49
	ds_write2_b64 v54, v[34:35], v[36:37] offset0:140 offset1:142
	v_or_b32_e32 v34, 0x60, v138
	v_cvt_pk_bf16_f32 v82, v82, v83
	v_cvt_pk_bf16_f32 v83, v84, v85
	v_cvt_pk_bf16_f32 v84, v86, v87
	v_mfma_f32_32x32x16_bf16 v[2:17], v[162:165], v[182:185], v[2:17]
	v_add_u32_e32 v86, 0x2000, v140
	s_nop 2
	v_cvt_pk_bf16_f32 v66, v66, v67
	v_cvt_pk_bf16_f32 v67, v68, v69
	v_cvt_pk_bf16_f32 v68, v70, v71
	v_cvt_pk_bf16_f32 v69, v72, v73
	v_mad_u64_u32 v[34:35], s[20:21], v34, s3, v[0:1]
	v_mfma_f32_32x32x16_bf16 v[114:129], v[158:161], v[170:173], v[114:129]
	s_nop 1
	v_cvt_pk_bf16_f32 v2, v2, v3
	v_cvt_pk_bf16_f32 v3, v4, v5
	v_cvt_pk_bf16_f32 v4, v6, v7
	v_cvt_pk_bf16_f32 v5, v8, v9
	v_lshrrev_b32_e32 v0, 1, v138
	ds_write2_b64 v86, v[66:67], v[68:69] offset0:72 offset1:74
	v_cvt_pk_bf16_f32 v66, v74, v75
	v_mfma_f32_32x32x16_bf16 v[98:113], v[162:165], v[170:173], v[98:113]
	v_cvt_pk_bf16_f32 v67, v76, v77
	v_cvt_pk_bf16_f32 v68, v78, v79
	v_cvt_pk_bf16_f32 v69, v80, v81
	ds_write2_b64 v34, v[2:3], v[4:5] offset0:8 offset1:10
	v_cvt_pk_bf16_f32 v2, v10, v11
	v_cvt_pk_bf16_f32 v3, v12, v13
	v_cvt_pk_bf16_f32 v4, v14, v15
	v_mfma_f32_32x32x16_bf16 v[18:33], v[158:161], v[182:185], v[18:33]
	v_cvt_pk_bf16_f32 v5, v16, v17
	v_and_b32_e32 v8, 16, v0
	v_and_b32_e32 v0, 0x3f0, v139
	ds_write2_b64 v86, v[66:67], v[68:69] offset0:76 offset1:78
	ds_write2_b64 v34, v[2:3], v[4:5] offset0:12 offset1:14
	v_lshl_add_u64 v[2:3], s[92:93], 0, v[0:1]
	v_bfe_u32 v0, v138, 6, 3
	v_lshl_or_b32 v4, v0, 5, v8
	v_or_b32_e32 v0, s19, v0
	v_cvt_pk_bf16_f32 v114, v114, v115
	v_cvt_pk_bf16_f32 v115, v116, v117
	v_cvt_pk_bf16_f32 v116, v118, v119
	v_cvt_pk_bf16_f32 v117, v120, v121
	v_cvt_pk_bf16_f32 v98, v98, v99
	v_cvt_pk_bf16_f32 v99, v100, v101
	v_cvt_pk_bf16_f32 v100, v102, v103
	v_cvt_pk_bf16_f32 v101, v104, v105
	v_cvt_pk_bf16_f32 v85, v88, v89
	v_cvt_pk_bf16_f32 v18, v18, v19
	v_cvt_pk_bf16_f32 v19, v20, v21
	v_cvt_pk_bf16_f32 v20, v22, v23
	v_cvt_pk_bf16_f32 v21, v24, v25
	v_lshlrev_b32_e32 v0, 10, v0
	ds_write2_b64 v140, v[114:115], v[116:117] offset1:2
	v_cvt_pk_bf16_f32 v114, v122, v123
	v_cvt_pk_bf16_f32 v115, v124, v125
	v_cvt_pk_bf16_f32 v116, v126, v127
	v_cvt_pk_bf16_f32 v117, v128, v129
	ds_write2_b64 v140, v[98:99], v[100:101] offset0:8 offset1:10
	v_cvt_pk_bf16_f32 v98, v106, v107
	v_cvt_pk_bf16_f32 v99, v108, v109
	v_cvt_pk_bf16_f32 v100, v110, v111
	v_cvt_pk_bf16_f32 v101, v112, v113
	ds_write2_b64 v86, v[82:83], v[84:85] offset0:64 offset1:66
	v_cvt_pk_bf16_f32 v82, v90, v91
	v_cvt_pk_bf16_f32 v83, v92, v93
	v_cvt_pk_bf16_f32 v84, v94, v95
	v_cvt_pk_bf16_f32 v85, v96, v97
	v_cvt_pk_bf16_f32 v51, v60, v61
	v_cvt_pk_bf16_f32 v52, v62, v63
	v_cvt_pk_bf16_f32 v53, v64, v65
	ds_write2_b64 v34, v[18:19], v[20:21] offset1:2
	v_cvt_pk_bf16_f32 v18, v26, v27
	v_cvt_pk_bf16_f32 v19, v28, v29
	v_cvt_pk_bf16_f32 v20, v30, v31
	v_cvt_pk_bf16_f32 v21, v32, v33
	v_and_b32_e32 v5, 31, v138
	v_lshl_add_u64 v[6:7], v[2:3], 0, v[0:1]
	s_mov_b32 s20, 0
	ds_write2_b64 v140, v[114:115], v[116:117] offset0:4 offset1:6
	ds_write2_b64 v140, v[98:99], v[100:101] offset0:12 offset1:14
	ds_write2_b64 v86, v[82:83], v[84:85] offset0:68 offset1:70
	ds_write2_b64 v54, v[50:51], v[52:53] offset0:132 offset1:134
	ds_write2_b64 v34, v[18:19], v[20:21] offset0:4 offset1:6
	s_waitcnt lgkmcnt(0)
	s_barrier

.LBB0_1555:
	s_mul_i32 s16, s13, 0x6000
	v_add_u32_e32 v146, s16, v144
	v_add_u32_e32 v147, s16, v142
	v_add_u32_e32 v198, v146, v131
	v_add_u32_e32 v199, v147, v131
	v_add_u32_e32 v200, v146, v141
	v_add_u32_e32 v201, v147, v141
	s_waitcnt vmcnt(6)
	s_barrier
	ds_read_b128 v[146:149], v198
	ds_read_b128 v[150:153], v198 offset:2048
	ds_read_b128 v[154:157], v199
	ds_read_b128 v[158:161], v199 offset:2048
	ds_read_b128 v[162:165], v199 offset:4096
	ds_read_b128 v[170:173], v199 offset:6144
	ds_read_b128 v[174:177], v200
	ds_read_b128 v[178:181], v200 offset:2048
	ds_read_b128 v[182:185], v201
	ds_read_b128 v[186:189], v201 offset:2048
	ds_read_b128 v[190:193], v201 offset:4096
	ds_read_b128 v[194:197], v201 offset:6144
	s_waitcnt lgkmcnt(0)
	v_mfma_f32_32x32x16_bf16 v[114:129], v[146:149], v[154:157], v[114:129]
	s_waitcnt vmcnt(0)
	s_barrier
	v_mfma_f32_32x32x16_bf16 v[82:97], v[146:149], v[158:161], v[82:97]
	v_mfma_f32_32x32x16_bf16 v[50:65], v[146:149], v[162:165], v[50:65]
	v_mfma_f32_32x32x16_bf16 v[18:33], v[146:149], v[170:173], v[18:33]
	s_add_i32 s14, s16, 0xffffa000
	s_cmp_gt_i32 s13, 0
	s_cselect_b32 s14, s14, 0xc000
	v_add_u32_e32 v148, s14, v145
	v_lshl_add_u64 v[138:139], v[134:135], 0, v[0:1]
	v_readfirstlane_b32 s14, v148
	v_add_u32_e32 v146, 0x1000, v148
	v_lshl_add_u64 v[136:137], v[138:139], 0, s[18:19]
	s_mov_b32 m0, s14
	v_readfirstlane_b32 s14, v146
	v_add_u32_e32 v146, 0x2000, v148
	global_load_lds_dwordx4 v[136:137], off
	v_mfma_f32_32x32x16_bf16 v[98:113], v[150:153], v[154:157], v[98:113]
	v_lshl_add_u64 v[136:137], v[138:139], 0, s[20:21]
	s_mov_b32 m0, s14
	v_readfirstlane_b32 s14, v146
	v_add_u32_e32 v146, 0x3000, v148
	global_load_lds_dwordx4 v[136:137], off
	v_mfma_f32_32x32x16_bf16 v[66:81], v[150:153], v[158:161], v[66:81]
	v_lshl_add_u64 v[136:137], v[138:139], 0, s[40:41]
	s_mov_b32 m0, s14
	v_readfirstlane_b32 s14, v146
	global_load_lds_dwordx4 v[136:137], off
	v_mfma_f32_32x32x16_bf16 v[34:49], v[150:153], v[162:165], v[34:49]
	v_lshl_add_u64 v[136:137], v[138:139], 0, s[42:43]
	s_mov_b32 m0, s14
	s_mov_b64 s[14:15], 0xf20000
	global_load_lds_dwordx4 v[136:137], off
	v_mfma_f32_32x32x16_bf16 v[2:17], v[150:153], v[170:173], v[2:17]
	v_lshl_add_u64 v[136:137], v[132:133], 0, v[0:1]
	v_add_u32_e32 v149, 0x4000, v148
	v_lshl_add_u64 v[146:147], v[136:137], 0, s[14:15]
	v_readfirstlane_b32 s14, v149
	s_mov_b32 m0, s14
	s_mov_b64 s[14:15], 0xf21000
	v_add_u32_e32 v148, 0x5000, v148
	global_load_lds_dwordx4 v[146:147], off
	v_mfma_f32_32x32x16_bf16 v[114:129], v[174:177], v[182:185], v[114:129]
	v_lshl_add_u64 v[146:147], v[136:137], 0, s[14:15]
	v_readfirstlane_b32 s14, v148
	s_mov_b32 m0, s14
	s_add_i32 s14, s13, 1
	s_cmp_lg_u32 s13, 2
	s_cselect_b32 s13, s14, 0
	s_mul_i32 s14, s13, 0x6000
	s_add_i32 s15, s14, 0xffffa000
	global_load_lds_dwordx4 v[146:147], off
	v_mfma_f32_32x32x16_bf16 v[98:113], v[178:181], v[182:185], v[98:113]
	s_cmp_gt_i32 s13, 0
	s_cselect_b32 s15, s15, 0xc000
	s_mov_b64 s[16:17], 0xf30000
	v_lshl_add_u64 v[132:133], v[132:133], 0, s[58:59]
	v_lshl_add_u64 v[134:135], v[134:135], 0, s[96:97]
	v_add_u32_e32 v148, s15, v145
	v_add_u32_e32 v149, 0x1000, v148
	v_readfirstlane_b32 s15, v148
	v_lshl_add_u64 v[146:147], v[138:139], 0, s[46:47]
	s_mov_b32 m0, s15
	v_readfirstlane_b32 s15, v149
	v_add_u32_e32 v149, 0x2000, v148
	global_load_lds_dwordx4 v[146:147], off
	v_mfma_f32_32x32x16_bf16 v[82:97], v[174:177], v[186:189], v[82:97]
	v_lshl_add_u64 v[146:147], v[138:139], 0, s[48:49]
	s_mov_b32 m0, s15
	v_readfirstlane_b32 s15, v149
	global_load_lds_dwordx4 v[146:147], off
	v_mfma_f32_32x32x16_bf16 v[66:81], v[178:181], v[186:189], v[66:81]
	v_lshl_add_u64 v[146:147], v[138:139], 0, s[50:51]
	s_mov_b32 m0, s15
	v_lshl_add_u64 v[138:139], v[138:139], 0, s[56:57]
	global_load_lds_dwordx4 v[146:147], off
	v_mfma_f32_32x32x16_bf16 v[50:65], v[174:177], v[190:193], v[50:65]
	v_add_u32_e32 v146, 0x3000, v148
	s_nop 0
	v_readfirstlane_b32 s15, v146
	v_add_u32_e32 v146, 0x4000, v148
	s_mov_b32 m0, s15
	v_readfirstlane_b32 s15, v146
	global_load_lds_dwordx4 v[138:139], off
	v_mfma_f32_32x32x16_bf16 v[34:49], v[178:181], v[190:193], v[34:49]
	v_lshl_add_u64 v[138:139], v[136:137], 0, s[16:17]
	s_mov_b32 m0, s15
	s_mov_b64 s[16:17], 0xf31000
	global_load_lds_dwordx4 v[138:139], off
	v_mfma_f32_32x32x16_bf16 v[18:33], v[174:177], v[194:197], v[18:33]
	v_add_u32_e32 v138, 0x5000, v148
	v_lshl_add_u64 v[136:137], v[136:137], 0, s[16:17]
	v_readfirstlane_b32 s15, v138
	s_mov_b32 m0, s15
	s_nop 0
	global_load_lds_dwordx4 v[136:137], off
	v_mfma_f32_32x32x16_bf16 v[2:17], v[178:181], v[194:197], v[2:17]
	v_add_u32_e32 v136, s14, v144
	v_add_u32_e32 v137, s14, v142
	s_add_i32 s14, s13, 1
	s_cmp_lg_u32 s13, 2
	s_cselect_b32 s13, s14, 0
	s_add_i32 s12, s12, -2
	s_cmp_eq_u32 s12, 0
	v_add_u32_e32 v194, v136, v131
	v_add_u32_e32 v195, v137, v131
	v_add_u32_e32 v196, v136, v141
	v_add_u32_e32 v197, v137, v141
	ds_read_b128 v[136:139], v194
	ds_read_b128 v[146:149], v194 offset:2048
	ds_read_b128 v[150:153], v195
	ds_read_b128 v[154:157], v195 offset:2048
	ds_read_b128 v[158:161], v195 offset:4096
	ds_read_b128 v[162:165], v195 offset:6144
	ds_read_b128 v[170:173], v196
	ds_read_b128 v[174:177], v196 offset:2048
	ds_read_b128 v[178:181], v197
	ds_read_b128 v[182:185], v197 offset:2048
	ds_read_b128 v[186:189], v197 offset:4096
	ds_read_b128 v[190:193], v197 offset:6144
	s_waitcnt lgkmcnt(0)
	s_nop 0
	v_mfma_f32_32x32x16_bf16 v[114:129], v[136:139], v[150:153], v[114:129]
	v_mfma_f32_32x32x16_bf16 v[98:113], v[146:149], v[150:153], v[98:113]
	v_mfma_f32_32x32x16_bf16 v[82:97], v[136:139], v[154:157], v[82:97]
	v_mfma_f32_32x32x16_bf16 v[66:81], v[146:149], v[154:157], v[66:81]
	v_mfma_f32_32x32x16_bf16 v[50:65], v[136:139], v[158:161], v[50:65]
	v_mfma_f32_32x32x16_bf16 v[34:49], v[146:149], v[158:161], v[34:49]
	v_mfma_f32_32x32x16_bf16 v[18:33], v[136:139], v[162:165], v[18:33]
	v_mfma_f32_32x32x16_bf16 v[2:17], v[146:149], v[162:165], v[2:17]
	v_mfma_f32_32x32x16_bf16 v[114:129], v[170:173], v[178:181], v[114:129]
	v_mfma_f32_32x32x16_bf16 v[98:113], v[174:177], v[178:181], v[98:113]
	v_mfma_f32_32x32x16_bf16 v[82:97], v[170:173], v[182:185], v[82:97]
	v_mfma_f32_32x32x16_bf16 v[66:81], v[174:177], v[182:185], v[66:81]
	v_mfma_f32_32x32x16_bf16 v[50:65], v[170:173], v[186:189], v[50:65]
	v_mfma_f32_32x32x16_bf16 v[34:49], v[174:177], v[186:189], v[34:49]
	v_mfma_f32_32x32x16_bf16 v[18:33], v[170:173], v[190:193], v[18:33]
	v_mfma_f32_32x32x16_bf16 v[2:17], v[174:177], v[190:193], v[2:17]
	s_cbranch_scc0 .LBB0_1555
	s_waitcnt vmcnt(6)
	s_barrier
	v_add_u32_e32 v0, v144, v131
	v_add_u32_e32 v164, v142, v131
	v_add_u32_e32 v165, v144, v141
	v_add_u32_e32 v190, v142, v141
	ds_read_b128 v[132:135], v0
	ds_read_b128 v[136:139], v0 offset:2048
	ds_read_b128 v[144:147], v164
	ds_read_b128 v[148:151], v164 offset:2048
	ds_read_b128 v[152:155], v164 offset:4096
	ds_read_b128 v[156:159], v164 offset:6144
	ds_read_b128 v[160:163], v165
	ds_read_b128 v[170:173], v165 offset:2048
	ds_read_b128 v[174:177], v190
	ds_read_b128 v[178:181], v190 offset:2048
	ds_read_b128 v[182:185], v190 offset:4096
	ds_read_b128 v[186:189], v190 offset:6144
	s_waitcnt lgkmcnt(0)
	v_or_b32_e32 v0, 0xa000, v143
	v_mfma_f32_32x32x16_bf16 v[114:129], v[132:135], v[144:147], v[114:129]
	s_waitcnt vmcnt(0)
	s_barrier
	s_movk_i32 s12, 0x80
	v_cmp_gt_u32_e64 s[48:49], s12, v130
	v_mfma_f32_32x32x16_bf16 v[98:113], v[136:139], v[144:147], v[98:113]
	v_mfma_f32_32x32x16_bf16 v[82:97], v[132:135], v[148:151], v[82:97]
	v_mfma_f32_32x32x16_bf16 v[66:81], v[136:139], v[148:151], v[66:81]
	v_mfma_f32_32x32x16_bf16 v[50:65], v[132:135], v[152:155], v[50:65]
	v_mfma_f32_32x32x16_bf16 v[34:49], v[136:139], v[152:155], v[34:49]
	v_mfma_f32_32x32x16_bf16 v[18:33], v[132:135], v[156:159], v[18:33]
	v_add_u32_e32 v132, 0x6000, v142
	v_mfma_f32_32x32x16_bf16 v[2:17], v[136:139], v[156:159], v[2:17]
	v_mfma_f32_32x32x16_bf16 v[114:129], v[160:163], v[174:177], v[114:129]
	v_mfma_f32_32x32x16_bf16 v[98:113], v[170:173], v[174:177], v[98:113]
	v_mfma_f32_32x32x16_bf16 v[82:97], v[160:163], v[178:181], v[82:97]
	v_mfma_f32_32x32x16_bf16 v[66:81], v[170:173], v[178:181], v[66:81]
	v_mfma_f32_32x32x16_bf16 v[50:65], v[160:163], v[182:185], v[50:65]
	v_mfma_f32_32x32x16_bf16 v[34:49], v[170:173], v[182:185], v[34:49]
	v_mfma_f32_32x32x16_bf16 v[18:33], v[160:163], v[186:189], v[18:33]
	v_mfma_f32_32x32x16_bf16 v[2:17], v[170:173], v[186:189], v[2:17]
	v_add_u32_e32 v186, v0, v131
	v_add_u32_e32 v131, v132, v131
	v_add_u32_e32 v0, v0, v141
	v_add_u32_e32 v141, v132, v141
	ds_read_b128 v[132:135], v186
	ds_read_b128 v[136:139], v186 offset:2048
	ds_read_b128 v[142:145], v131
	ds_read_b128 v[146:149], v131 offset:2048
	ds_read_b128 v[150:153], v131 offset:4096
	ds_read_b128 v[154:157], v131 offset:6144
	ds_read_b128 v[158:161], v0
	ds_read_b128 v[162:165], v0 offset:2048
	ds_read_b128 v[170:173], v141
	ds_read_b128 v[174:177], v141 offset:2048
	ds_read_b128 v[178:181], v141 offset:4096
	ds_read_b128 v[182:185], v141 offset:6144
	s_waitcnt lgkmcnt(0)
	s_waitcnt vmcnt(0) lgkmcnt(0)
	s_barrier
	v_mfma_f32_32x32x16_bf16 v[114:129], v[132:135], v[142:145], v[114:129]
	v_mfma_f32_32x32x16_bf16 v[98:113], v[136:139], v[142:145], v[98:113]
	v_and_b32_e32 v143, 64, v130
	v_and_b32_e32 v144, 31, v130
	v_mfma_f32_32x32x16_bf16 v[82:97], v[132:135], v[146:149], v[82:97]
	v_mfma_f32_32x32x16_bf16 v[66:81], v[136:139], v[146:149], v[66:81]
	v_mfma_f32_32x32x16_bf16 v[50:65], v[132:135], v[150:153], v[50:65]
	v_mfma_f32_32x32x16_bf16 v[34:49], v[136:139], v[150:153], v[34:49]
	v_mfma_f32_32x32x16_bf16 v[18:33], v[132:135], v[154:157], v[18:33]
	v_mfma_f32_32x32x16_bf16 v[2:17], v[136:139], v[154:157], v[2:17]
	v_mfma_f32_32x32x16_bf16 v[114:129], v[158:161], v[170:173], v[114:129]
	v_mfma_f32_32x32x16_bf16 v[98:113], v[162:165], v[170:173], v[98:113]
	v_mfma_f32_32x32x16_bf16 v[82:97], v[158:161], v[174:177], v[82:97]
	v_mfma_f32_32x32x16_bf16 v[66:81], v[162:165], v[174:177], v[66:81]
	v_mfma_f32_32x32x16_bf16 v[50:65], v[158:161], v[178:181], v[50:65]
	v_mfma_f32_32x32x16_bf16 v[34:49], v[162:165], v[178:181], v[34:49]
	v_mfma_f32_32x32x16_bf16 v[18:33], v[158:161], v[182:185], v[18:33]
	v_mfma_f32_32x32x16_bf16 v[2:17], v[162:165], v[182:185], v[2:17]
	s_and_saveexec_b64 s[12:13], s[48:49]
	s_cbranch_execz .LBB0_1558
	v_mul_u32_u24_e32 v0, 0x210, v144
	v_lshlrev_b32_e32 v131, 4, v140
	v_lshlrev_b32_e32 v132, 2, v143
	v_add3_u32 v0, v0, v131, v132
	ds_write_b128 v0, v[114:117]
	ds_write_b128 v0, v[118:121] offset:32
	ds_write_b128 v0, v[122:125] offset:64
	ds_write_b128 v0, v[126:129] offset:96
	ds_write_b128 v0, v[98:101] offset:128
	ds_write_b128 v0, v[102:105] offset:160
	ds_write_b128 v0, v[106:109] offset:192
	ds_write_b128 v0, v[110:113] offset:224
	ds_write_b128 v0, v[82:85] offset:16896
	ds_write_b128 v0, v[86:89] offset:16928
	ds_write_b128 v0, v[90:93] offset:16960
	ds_write_b128 v0, v[94:97] offset:16992
	ds_write_b128 v0, v[66:69] offset:17024
	ds_write_b128 v0, v[70:73] offset:17056
	ds_write_b128 v0, v[74:77] offset:17088
	ds_write_b128 v0, v[78:81] offset:17120
	ds_write_b128 v0, v[50:53] offset:33792
	ds_write_b128 v0, v[54:57] offset:33824
	ds_write_b128 v0, v[58:61] offset:33856
	ds_write_b128 v0, v[62:65] offset:33888
	ds_write_b128 v0, v[34:37] offset:33920
	ds_write_b128 v0, v[38:41] offset:33952
	ds_write_b128 v0, v[42:45] offset:33984
	ds_write_b128 v0, v[46:49] offset:34016
	v_or_b32_e32 v0, 0x60, v130
	v_mul_lo_u32 v0, v0, s94
	v_add3_u32 v0, v0, v131, v132
	ds_write_b128 v0, v[18:21]
	ds_write_b128 v0, v[22:25] offset:32
	ds_write_b128 v0, v[26:29] offset:64
	ds_write_b128 v0, v[30:33] offset:96
	ds_write_b128 v0, v[2:5] offset:128
	ds_write_b128 v0, v[6:9] offset:160
	ds_write_b128 v0, v[10:13] offset:192
	ds_write_b128 v0, v[14:17] offset:224

.LBB0_1654:
	s_mul_i32 s22, s19, 0x6000
	v_add_u32_e32 v146, s22, v144
	v_add_u32_e32 v147, s22, v142
	v_add_u32_e32 v198, v146, v141
	v_add_u32_e32 v199, v147, v141
	v_add_u32_e32 v200, v146, v140
	v_add_u32_e32 v201, v147, v140
	s_waitcnt vmcnt(6)
	s_barrier
	ds_read_b128 v[146:149], v198
	ds_read_b128 v[150:153], v198 offset:2048
	ds_read_b128 v[154:157], v199
	ds_read_b128 v[158:161], v199 offset:2048
	ds_read_b128 v[162:165], v199 offset:4096
	ds_read_b128 v[170:173], v199 offset:6144
	ds_read_b128 v[174:177], v200
	ds_read_b128 v[178:181], v200 offset:2048
	ds_read_b128 v[182:185], v201
	ds_read_b128 v[186:189], v201 offset:2048
	ds_read_b128 v[190:193], v201 offset:4096
	ds_read_b128 v[194:197], v201 offset:6144
	s_waitcnt lgkmcnt(0)
	v_mfma_f32_32x32x16_bf16 v[114:129], v[146:149], v[154:157], v[114:129]
	s_waitcnt vmcnt(0)
	s_barrier
	v_mfma_f32_32x32x16_bf16 v[82:97], v[146:149], v[158:161], v[82:97]
	v_mfma_f32_32x32x16_bf16 v[50:65], v[146:149], v[162:165], v[50:65]
	v_mfma_f32_32x32x16_bf16 v[18:33], v[146:149], v[170:173], v[18:33]
	s_add_i32 s20, s22, 0xffffa000
	s_cmp_gt_i32 s19, 0
	s_cselect_b32 s20, s20, 0xc000
	v_add_u32_e32 v148, s20, v145
	v_lshl_add_u64 v[136:137], v[132:133], 0, v[0:1]
	v_readfirstlane_b32 s20, v148
	v_add_u32_e32 v146, 0x1000, v148
	v_lshl_add_u64 v[134:135], v[136:137], 0, s[34:35]
	s_mov_b32 m0, s20
	v_readfirstlane_b32 s20, v146
	v_add_u32_e32 v146, 0x2000, v148
	global_load_lds_dwordx4 v[134:135], off
	v_mfma_f32_32x32x16_bf16 v[98:113], v[150:153], v[154:157], v[98:113]
	v_lshl_add_u64 v[134:135], v[136:137], 0, s[36:37]
	s_mov_b32 m0, s20
	v_readfirstlane_b32 s20, v146
	v_add_u32_e32 v146, 0x3000, v148
	global_load_lds_dwordx4 v[134:135], off
	v_mfma_f32_32x32x16_bf16 v[66:81], v[150:153], v[158:161], v[66:81]
	v_lshl_add_u64 v[134:135], v[136:137], 0, s[38:39]
	s_mov_b32 m0, s20
	v_readfirstlane_b32 s20, v146
	global_load_lds_dwordx4 v[134:135], off
	v_mfma_f32_32x32x16_bf16 v[34:49], v[150:153], v[162:165], v[34:49]
	v_lshl_add_u64 v[134:135], v[136:137], 0, s[40:41]
	s_mov_b32 m0, s20
	s_mov_b64 s[20:21], 0x1180000
	global_load_lds_dwordx4 v[134:135], off
	v_mfma_f32_32x32x16_bf16 v[2:17], v[150:153], v[170:173], v[2:17]
	v_lshl_add_u64 v[134:135], v[130:131], 0, v[0:1]
	v_add_u32_e32 v149, 0x4000, v148
	v_lshl_add_u64 v[146:147], v[134:135], 0, s[20:21]
	v_readfirstlane_b32 s20, v149
	s_mov_b32 m0, s20
	s_mov_b64 s[20:21], 0x1181000
	v_add_u32_e32 v148, 0x5000, v148
	global_load_lds_dwordx4 v[146:147], off
	v_mfma_f32_32x32x16_bf16 v[114:129], v[174:177], v[182:185], v[114:129]
	v_lshl_add_u64 v[146:147], v[134:135], 0, s[20:21]
	v_readfirstlane_b32 s20, v148
	s_mov_b32 m0, s20
	s_add_i32 s20, s19, 1
	s_cmp_lg_u32 s19, 2
	s_cselect_b32 s19, s20, 0
	s_mul_i32 s20, s19, 0x6000
	s_add_i32 s21, s20, 0xffffa000
	global_load_lds_dwordx4 v[146:147], off
	v_mfma_f32_32x32x16_bf16 v[98:113], v[178:181], v[182:185], v[98:113]
	s_cmp_gt_i32 s19, 0
	s_cselect_b32 s21, s21, 0xc000
	s_mov_b64 s[22:23], 0x11c0000
	v_lshl_add_u64 v[132:133], v[132:133], 0, s[96:97]
	v_add_u32_e32 v148, s21, v145
	v_add_u32_e32 v149, 0x1000, v148
	v_readfirstlane_b32 s21, v148
	v_lshl_add_u64 v[146:147], v[136:137], 0, s[88:89]
	s_mov_b32 m0, s21
	v_readfirstlane_b32 s21, v149
	v_add_u32_e32 v149, 0x2000, v148
	global_load_lds_dwordx4 v[146:147], off
	v_mfma_f32_32x32x16_bf16 v[82:97], v[174:177], v[186:189], v[82:97]
	v_lshl_add_u64 v[146:147], v[136:137], 0, s[4:5]
	s_mov_b32 m0, s21
	v_readfirstlane_b32 s21, v149
	global_load_lds_dwordx4 v[146:147], off
	v_mfma_f32_32x32x16_bf16 v[66:81], v[178:181], v[186:189], v[66:81]
	v_lshl_add_u64 v[146:147], v[136:137], 0, s[84:85]
	s_mov_b32 m0, s21
	v_lshl_add_u64 v[136:137], v[136:137], 0, s[86:87]
	global_load_lds_dwordx4 v[146:147], off
	v_mfma_f32_32x32x16_bf16 v[50:65], v[174:177], v[190:193], v[50:65]
	v_add_u32_e32 v146, 0x3000, v148
	s_nop 0
	v_readfirstlane_b32 s21, v146
	v_add_u32_e32 v146, 0x4000, v148
	s_mov_b32 m0, s21
	v_readfirstlane_b32 s21, v146
	global_load_lds_dwordx4 v[136:137], off
	v_mfma_f32_32x32x16_bf16 v[34:49], v[178:181], v[190:193], v[34:49]
	v_lshl_add_u64 v[136:137], v[134:135], 0, s[22:23]
	s_mov_b32 m0, s21
	s_mov_b64 s[22:23], 0x11c1000
	global_load_lds_dwordx4 v[136:137], off
	v_mfma_f32_32x32x16_bf16 v[18:33], v[174:177], v[194:197], v[18:33]
	v_add_u32_e32 v136, 0x5000, v148
	v_lshl_add_u64 v[134:135], v[134:135], 0, s[22:23]
	v_readfirstlane_b32 s21, v136
	s_mov_b32 m0, s21
	s_nop 0
	global_load_lds_dwordx4 v[134:135], off
	v_mfma_f32_32x32x16_bf16 v[2:17], v[178:181], v[194:197], v[2:17]
	v_add_u32_e32 v134, s20, v144
	v_add_u32_e32 v135, s20, v142
	s_add_i32 s20, s19, 1
	s_cmp_lg_u32 s19, 2
	s_cselect_b32 s19, s20, 0
	s_add_i32 s18, s18, -2
	s_mov_b64 s[20:21], 0x80000
	v_lshl_add_u64 v[130:131], v[130:131], 0, s[20:21]
	s_cmp_eq_u32 s18, 0
	v_add_u32_e32 v194, v134, v141
	v_add_u32_e32 v195, v135, v141
	v_add_u32_e32 v196, v134, v140
	v_add_u32_e32 v197, v135, v140
	ds_read_b128 v[134:137], v194
	ds_read_b128 v[146:149], v194 offset:2048
	ds_read_b128 v[150:153], v195
	ds_read_b128 v[154:157], v195 offset:2048
	ds_read_b128 v[158:161], v195 offset:4096
	ds_read_b128 v[162:165], v195 offset:6144
	ds_read_b128 v[170:173], v196
	ds_read_b128 v[174:177], v196 offset:2048
	ds_read_b128 v[178:181], v197
	ds_read_b128 v[182:185], v197 offset:2048
	ds_read_b128 v[186:189], v197 offset:4096
	ds_read_b128 v[190:193], v197 offset:6144
	s_waitcnt lgkmcnt(0)
	s_nop 0
	v_mfma_f32_32x32x16_bf16 v[114:129], v[134:137], v[150:153], v[114:129]
	v_mfma_f32_32x32x16_bf16 v[98:113], v[146:149], v[150:153], v[98:113]
	v_mfma_f32_32x32x16_bf16 v[82:97], v[134:137], v[154:157], v[82:97]
	v_mfma_f32_32x32x16_bf16 v[66:81], v[146:149], v[154:157], v[66:81]
	v_mfma_f32_32x32x16_bf16 v[50:65], v[134:137], v[158:161], v[50:65]
	v_mfma_f32_32x32x16_bf16 v[34:49], v[146:149], v[158:161], v[34:49]
	v_mfma_f32_32x32x16_bf16 v[18:33], v[134:137], v[162:165], v[18:33]
	v_mfma_f32_32x32x16_bf16 v[2:17], v[146:149], v[162:165], v[2:17]
	v_mfma_f32_32x32x16_bf16 v[114:129], v[170:173], v[178:181], v[114:129]
	v_mfma_f32_32x32x16_bf16 v[98:113], v[174:177], v[178:181], v[98:113]
	v_mfma_f32_32x32x16_bf16 v[82:97], v[170:173], v[182:185], v[82:97]
	v_mfma_f32_32x32x16_bf16 v[66:81], v[174:177], v[182:185], v[66:81]
	v_mfma_f32_32x32x16_bf16 v[50:65], v[170:173], v[186:189], v[50:65]
	v_mfma_f32_32x32x16_bf16 v[34:49], v[174:177], v[186:189], v[34:49]
	v_mfma_f32_32x32x16_bf16 v[18:33], v[170:173], v[190:193], v[18:33]
	v_mfma_f32_32x32x16_bf16 v[2:17], v[174:177], v[190:193], v[2:17]
	s_cbranch_scc0 .LBB0_1654
	s_waitcnt vmcnt(6)
	s_barrier
	v_add_u32_e32 v0, v144, v141
	v_add_u32_e32 v164, v142, v141
	v_add_u32_e32 v165, v144, v140
	v_add_u32_e32 v190, v142, v140
	ds_read_b128 v[130:133], v0
	ds_read_b128 v[134:137], v0 offset:2048
	ds_read_b128 v[144:147], v164
	ds_read_b128 v[148:151], v164 offset:2048
	ds_read_b128 v[152:155], v164 offset:4096
	ds_read_b128 v[156:159], v164 offset:6144
	ds_read_b128 v[160:163], v165
	ds_read_b128 v[170:173], v165 offset:2048
	ds_read_b128 v[174:177], v190
	ds_read_b128 v[178:181], v190 offset:2048
	ds_read_b128 v[182:185], v190 offset:4096
	ds_read_b128 v[186:189], v190 offset:6144
	s_waitcnt lgkmcnt(0)
	v_or_b32_e32 v0, 0xa000, v143
	v_mfma_f32_32x32x16_bf16 v[34:49], v[134:137], v[152:155], v[34:49]
	s_waitcnt vmcnt(0)
	s_barrier
	v_add_u32_e32 v164, v141, v0
	v_add_u32_e32 v0, v140, v0
	v_mfma_f32_32x32x16_bf16 v[50:65], v[130:133], v[152:155], v[50:65]
	v_mfma_f32_32x32x16_bf16 v[114:129], v[130:133], v[144:147], v[114:129]
	v_mfma_f32_32x32x16_bf16 v[98:113], v[134:137], v[144:147], v[98:113]
	v_mfma_f32_32x32x16_bf16 v[82:97], v[130:133], v[148:151], v[82:97]
	v_mfma_f32_32x32x16_bf16 v[66:81], v[134:137], v[148:151], v[66:81]
	v_mfma_f32_32x32x16_bf16 v[18:33], v[130:133], v[156:159], v[18:33]
	v_add_u32_e32 v130, 0x6000, v142
	v_add_u32_e32 v165, v141, v130
	v_mfma_f32_32x32x16_bf16 v[2:17], v[134:137], v[156:159], v[2:17]
	v_mfma_f32_32x32x16_bf16 v[34:49], v[170:173], v[182:185], v[34:49]
	v_mfma_f32_32x32x16_bf16 v[50:65], v[160:163], v[182:185], v[50:65]
	v_mfma_f32_32x32x16_bf16 v[114:129], v[160:163], v[174:177], v[114:129]
	v_mfma_f32_32x32x16_bf16 v[98:113], v[170:173], v[174:177], v[98:113]
	v_mfma_f32_32x32x16_bf16 v[82:97], v[160:163], v[178:181], v[82:97]
	v_mfma_f32_32x32x16_bf16 v[66:81], v[170:173], v[178:181], v[66:81]
	v_mfma_f32_32x32x16_bf16 v[18:33], v[160:163], v[186:189], v[18:33]
	v_mfma_f32_32x32x16_bf16 v[2:17], v[170:173], v[186:189], v[2:17]
	v_add_u32_e32 v186, v140, v130
	ds_read_b128 v[130:133], v164
	ds_read_b128 v[134:137], v164 offset:2048
	ds_read_b128 v[140:143], v165
	ds_read_b128 v[144:147], v165 offset:2048
	ds_read_b128 v[148:151], v165 offset:4096
	ds_read_b128 v[152:155], v165 offset:6144
	ds_read_b128 v[156:159], v0
	ds_read_b128 v[160:163], v0 offset:2048
	ds_read_b128 v[170:173], v186
	ds_read_b128 v[174:177], v186 offset:2048
	ds_read_b128 v[178:181], v186 offset:4096
	ds_read_b128 v[182:185], v186 offset:6144
	s_waitcnt lgkmcnt(0)
	v_lshlrev_b32_e32 v0, 1, v138
	v_and_b32_e32 v0, 0x80, v0
	v_lshl_or_b32 v0, v139, 3, v0
	s_waitcnt vmcnt(0) lgkmcnt(0)
	s_barrier
	v_mfma_f32_32x32x16_bf16 v[34:49], v[134:137], v[148:151], v[34:49]
	v_mfma_f32_32x32x16_bf16 v[50:65], v[130:133], v[148:151], v[50:65]
	v_mfma_f32_32x32x16_bf16 v[34:49], v[160:163], v[178:181], v[34:49]
	v_mfma_f32_32x32x16_bf16 v[50:65], v[156:159], v[178:181], v[50:65]
	s_nop 10
	v_max_f32_e32 v34, v34, v34
	v_max_f32_e32 v35, v35, v35
	v_max_f32_e32 v36, v36, v36
	v_max_f32_e32 v37, v37, v37
	v_max_f32_e32 v34, 0, v34
	v_max_f32_e32 v35, 0, v35
	v_max_f32_e32 v36, 0, v36
	v_mfma_f32_32x32x16_bf16 v[18:33], v[130:133], v[152:155], v[18:33]
	v_max_f32_e32 v37, 0, v37
	v_mul_f32_e64 v34, v34, v34
	v_mul_f32_e64 v35, v35, v35
	v_mul_f32_e64 v36, v36, v36
	v_mul_f32_e64 v37, v37, v37
	v_max_f32_e32 v50, v50, v50
	v_max_f32_e32 v51, v51, v51
	v_max_f32_e32 v52, v52, v52
	v_max_f32_e32 v53, v53, v53
	v_cvt_pk_bf16_f32 v34, v34, v35
	v_cvt_pk_bf16_f32 v35, v36, v37
	v_max_f32_e32 v36, v38, v38
	v_max_f32_e32 v37, v39, v39
	v_max_f32_e32 v38, v40, v40
	v_max_f32_e32 v39, v41, v41
	v_mfma_f32_32x32x16_bf16 v[114:129], v[130:133], v[140:143], v[114:129]
	v_max_f32_e32 v50, 0, v50
	v_max_f32_e32 v51, 0, v51
	v_max_f32_e32 v52, 0, v52
	v_max_f32_e32 v53, 0, v53
	v_max_f32_e32 v36, 0, v36
	v_max_f32_e32 v37, 0, v37
	v_max_f32_e32 v38, 0, v38
	v_mfma_f32_32x32x16_bf16 v[82:97], v[130:133], v[144:147], v[82:97]
	v_and_b32_e32 v130, 0xfffff9f, v138
	v_max_f32_e32 v39, 0, v39
	v_mad_u64_u32 v[130:131], s[18:19], v130, s3, v[0:1]
	v_mul_f32_e64 v50, v50, v50
	v_mul_f32_e64 v51, v51, v51
	v_pk_mul_f32 v[52:53], v[52:53], v[52:53]
	v_pk_mul_f32 v[36:37], v[36:37], v[36:37]
	v_pk_mul_f32 v[38:39], v[38:39], v[38:39]
	v_cvt_pk_bf16_f32 v50, v50, v51
	v_cvt_pk_bf16_f32 v51, v52, v53
	v_max_f32_e32 v52, v54, v54
	v_max_f32_e32 v54, v56, v56
	v_add_u32_e32 v56, 0x4000, v130
	v_cvt_pk_bf16_f32 v36, v36, v37
	v_cvt_pk_bf16_f32 v37, v38, v39
	v_mfma_f32_32x32x16_bf16 v[18:33], v[156:159], v[182:185], v[18:33]
	ds_write2_b64 v56, v[34:35], v[36:37] offset0:136 offset1:138
	v_max_f32_e32 v34, v42, v42
	v_max_f32_e32 v35, v43, v43
	v_max_f32_e32 v36, v44, v44
	v_max_f32_e32 v37, v45, v45
	v_max_f32_e32 v34, 0, v34
	v_max_f32_e32 v35, 0, v35
	v_max_f32_e32 v36, 0, v36
	v_max_f32_e32 v37, 0, v37
	v_pk_mul_f32 v[34:35], v[34:35], v[34:35]
	v_pk_mul_f32 v[36:37], v[36:37], v[36:37]
	v_cvt_pk_bf16_f32 v34, v34, v35
	v_cvt_pk_bf16_f32 v35, v36, v37
	v_max_f32_e32 v36, v46, v46
	v_max_f32_e32 v37, v47, v47
	v_max_f32_e32 v38, v48, v48
	v_max_f32_e32 v39, v49, v49
	v_max_f32_e32 v36, 0, v36
	v_max_f32_e32 v37, 0, v37
	v_max_f32_e32 v38, 0, v38
	v_max_f32_e32 v39, 0, v39
	v_mfma_f32_32x32x16_bf16 v[82:97], v[156:159], v[174:177], v[82:97]
	v_mul_f32_e64 v36, v36, v36
	v_mul_f32_e64 v37, v37, v37
	v_mul_f32_e64 v38, v38, v38
	v_mul_f32_e64 v39, v39, v39
	v_cvt_pk_bf16_f32 v36, v36, v37
	v_cvt_pk_bf16_f32 v37, v38, v39
	ds_write2_b64 v56, v[34:35], v[36:37] offset0:140 offset1:142
	v_or_b32_e32 v34, 0x60, v138
	v_mad_u64_u32 v[34:35], s[18:19], v34, s3, v[0:1]
	v_max_f32_e32 v0, v18, v18
	v_max_f32_e32 v18, 0, v0
	v_max_f32_e32 v0, v19, v19
	v_max_f32_e32 v19, 0, v0
	v_max_f32_e32 v0, v20, v20
	v_max_f32_e32 v20, 0, v0
	v_max_f32_e32 v0, v21, v21
	v_mfma_f32_32x32x16_bf16 v[2:17], v[134:137], v[152:155], v[2:17]
	v_max_f32_e32 v21, 0, v0
	v_max_f32_e32 v82, v82, v82
	v_max_f32_e32 v83, v83, v83
	v_max_f32_e32 v84, v84, v84
	v_max_f32_e32 v85, v85, v85
	v_pk_mul_f32 v[18:19], v[18:19], v[18:19]
	v_pk_mul_f32 v[20:21], v[20:21], v[20:21]
	v_max_f32_e32 v0, v22, v22
	v_max_f32_e32 v82, 0, v82
	v_max_f32_e32 v83, 0, v83
	v_max_f32_e32 v84, 0, v84
	v_max_f32_e32 v85, 0, v85
	v_cvt_pk_bf16_f32 v18, v18, v19
	v_cvt_pk_bf16_f32 v19, v20, v21
	v_max_f32_e32 v20, 0, v0
	v_max_f32_e32 v0, v23, v23
	v_pk_mul_f32 v[82:83], v[82:83], v[82:83]
	v_pk_mul_f32 v[84:85], v[84:85], v[84:85]
	v_max_f32_e32 v21, 0, v0
	v_max_f32_e32 v0, v24, v24
	v_cvt_pk_bf16_f32 v82, v82, v83
	v_cvt_pk_bf16_f32 v83, v84, v85
	v_max_f32_e32 v84, v86, v86
	v_max_f32_e32 v85, v87, v87
	v_max_f32_e32 v86, v88, v88
	v_max_f32_e32 v87, v89, v89
	v_max_f32_e32 v53, v55, v55
	v_max_f32_e32 v55, v57, v57
	v_max_f32_e32 v22, 0, v0
	v_max_f32_e32 v0, v25, v25
	v_mfma_f32_32x32x16_bf16 v[66:81], v[134:137], v[144:147], v[66:81]
	v_max_f32_e32 v84, 0, v84
	v_max_f32_e32 v85, 0, v85
	v_max_f32_e32 v86, 0, v86
	v_max_f32_e32 v87, 0, v87
	v_max_f32_e32 v52, 0, v52
	v_max_f32_e32 v53, 0, v53
	v_max_f32_e32 v54, 0, v54
	v_max_f32_e32 v55, 0, v55
	v_max_f32_e32 v23, 0, v0
	v_pk_mul_f32 v[84:85], v[84:85], v[84:85]
	v_pk_mul_f32 v[86:87], v[86:87], v[86:87]
	v_pk_mul_f32 v[52:53], v[52:53], v[52:53]
	v_pk_mul_f32 v[54:55], v[54:55], v[54:55]
	v_pk_mul_f32 v[20:21], v[20:21], v[20:21]
	v_pk_mul_f32 v[22:23], v[22:23], v[22:23]
	v_cvt_pk_bf16_f32 v84, v84, v85
	v_cvt_pk_bf16_f32 v85, v86, v87
	v_add_u32_e32 v88, 0x2000, v130
	v_cvt_pk_bf16_f32 v52, v52, v53
	v_cvt_pk_bf16_f32 v53, v54, v55
	v_cvt_pk_bf16_f32 v20, v20, v21
	v_cvt_pk_bf16_f32 v21, v22, v23
	v_max_f32_e32 v0, v26, v26
	v_mfma_f32_32x32x16_bf16 v[2:17], v[160:163], v[182:185], v[2:17]
	ds_write2_b64 v88, v[82:83], v[84:85] offset0:64 offset1:66
	ds_write2_b64 v56, v[50:51], v[52:53] offset0:128 offset1:130
	ds_write2_b64 v34, v[18:19], v[20:21] offset1:2
	v_max_f32_e32 v18, 0, v0
	v_max_f32_e32 v0, v27, v27
	v_max_f32_e32 v19, 0, v0
	v_max_f32_e32 v0, v28, v28
	v_max_f32_e32 v20, 0, v0
	v_max_f32_e32 v0, v29, v29
	v_max_f32_e32 v21, 0, v0
	v_mfma_f32_32x32x16_bf16 v[98:113], v[134:137], v[140:143], v[98:113]
	v_mul_f32_e64 v18, v18, v18
	v_mul_f32_e64 v19, v19, v19
	v_mul_f32_e64 v20, v20, v20
	v_mul_f32_e64 v21, v21, v21
	v_max_f32_e32 v0, v30, v30
	v_cvt_pk_bf16_f32 v18, v18, v19
	v_cvt_pk_bf16_f32 v19, v20, v21
	v_max_f32_e32 v20, 0, v0
	v_max_f32_e32 v0, v31, v31
	v_mfma_f32_32x32x16_bf16 v[66:81], v[160:163], v[174:177], v[66:81]
	v_max_f32_e32 v21, 0, v0
	v_max_f32_e32 v0, v32, v32
	v_max_f32_e32 v22, 0, v0
	v_max_f32_e32 v0, v33, v33
	v_max_f32_e32 v23, 0, v0
	v_max_f32_e32 v0, v2, v2
	v_max_f32_e32 v2, 0, v0
	v_max_f32_e32 v0, v3, v3
	v_max_f32_e32 v3, 0, v0
	v_max_f32_e32 v0, v4, v4
	v_max_f32_e32 v4, 0, v0
	v_max_f32_e32 v0, v5, v5
	v_mfma_f32_32x32x16_bf16 v[114:129], v[156:159], v[170:173], v[114:129]
	v_max_f32_e32 v5, 0, v0
	v_max_f32_e32 v66, v66, v66
	v_max_f32_e32 v67, v67, v67
	v_max_f32_e32 v68, v68, v68
	v_max_f32_e32 v69, v69, v69
	v_pk_mul_f32 v[2:3], v[2:3], v[2:3]
	v_pk_mul_f32 v[4:5], v[4:5], v[4:5]
	v_mfma_f32_32x32x16_bf16 v[98:113], v[160:163], v[170:173], v[98:113]
	v_max_f32_e32 v0, v6, v6
	v_max_f32_e32 v66, 0, v66
	v_max_f32_e32 v67, 0, v67
	v_max_f32_e32 v68, 0, v68
	v_max_f32_e32 v69, 0, v69
	v_cvt_pk_bf16_f32 v2, v2, v3
	v_cvt_pk_bf16_f32 v3, v4, v5
	v_max_f32_e32 v4, 0, v0
	v_max_f32_e32 v0, v7, v7
	v_pk_mul_f32 v[66:67], v[66:67], v[66:67]
	v_pk_mul_f32 v[68:69], v[68:69], v[68:69]
	v_max_f32_e32 v5, 0, v0
	v_max_f32_e32 v0, v8, v8
	v_cvt_pk_bf16_f32 v66, v66, v67
	v_cvt_pk_bf16_f32 v67, v68, v69
	v_max_f32_e32 v68, v70, v70
	v_max_f32_e32 v69, v71, v71
	v_max_f32_e32 v70, v72, v72
	v_max_f32_e32 v71, v73, v73
	v_max_f32_e32 v6, 0, v0
	v_max_f32_e32 v0, v9, v9
	v_max_f32_e32 v68, 0, v68
	v_max_f32_e32 v69, 0, v69
	v_max_f32_e32 v70, 0, v70
	v_max_f32_e32 v71, 0, v71
	v_max_f32_e32 v7, 0, v0
	v_pk_mul_f32 v[68:69], v[68:69], v[68:69]
	v_pk_mul_f32 v[70:71], v[70:71], v[70:71]
	v_pk_mul_f32 v[4:5], v[4:5], v[4:5]
	v_pk_mul_f32 v[6:7], v[6:7], v[6:7]
	v_cvt_pk_bf16_f32 v68, v68, v69
	v_cvt_pk_bf16_f32 v69, v70, v71
	v_cvt_pk_bf16_f32 v4, v4, v5
	v_cvt_pk_bf16_f32 v5, v6, v7
	v_max_f32_e32 v0, v10, v10
	v_max_f32_e32 v114, v114, v114
	v_max_f32_e32 v115, v115, v115
	v_max_f32_e32 v116, v116, v116
	v_max_f32_e32 v117, v117, v117
	v_max_f32_e32 v98, v98, v98
	v_max_f32_e32 v99, v99, v99
	v_max_f32_e32 v100, v100, v100
	v_max_f32_e32 v101, v101, v101
	ds_write2_b64 v88, v[66:67], v[68:69] offset0:72 offset1:74
	ds_write2_b64 v34, v[2:3], v[4:5] offset0:8 offset1:10
	v_max_f32_e32 v2, 0, v0
	v_max_f32_e32 v0, v11, v11
	v_max_f32_e32 v114, 0, v114
	v_max_f32_e32 v115, 0, v115
	v_max_f32_e32 v116, 0, v116
	v_max_f32_e32 v117, 0, v117
	v_max_f32_e32 v98, 0, v98
	v_max_f32_e32 v99, 0, v99
	v_max_f32_e32 v100, 0, v100
	v_max_f32_e32 v101, 0, v101
	v_max_f32_e32 v3, 0, v0
	v_max_f32_e32 v0, v12, v12
	v_pk_mul_f32 v[114:115], v[114:115], v[114:115]
	v_pk_mul_f32 v[116:117], v[116:117], v[116:117]
	v_pk_mul_f32 v[98:99], v[98:99], v[98:99]
	v_pk_mul_f32 v[100:101], v[100:101], v[100:101]
	v_max_f32_e32 v4, 0, v0
	v_max_f32_e32 v0, v13, v13
	v_cvt_pk_bf16_f32 v114, v114, v115
	v_cvt_pk_bf16_f32 v115, v116, v117
	v_max_f32_e32 v116, v118, v118
	v_max_f32_e32 v117, v119, v119
	v_max_f32_e32 v118, v120, v120
	v_max_f32_e32 v119, v121, v121
	v_cvt_pk_bf16_f32 v98, v98, v99
	v_cvt_pk_bf16_f32 v99, v100, v101
	v_max_f32_e32 v100, v102, v102
	v_max_f32_e32 v101, v103, v103
	v_max_f32_e32 v102, v104, v104
	v_max_f32_e32 v103, v105, v105
	v_max_f32_e32 v5, 0, v0
	v_max_f32_e32 v116, 0, v116
	v_max_f32_e32 v117, 0, v117
	v_max_f32_e32 v118, 0, v118
	v_max_f32_e32 v119, 0, v119
	v_max_f32_e32 v100, 0, v100
	v_max_f32_e32 v101, 0, v101
	v_max_f32_e32 v102, 0, v102
	v_max_f32_e32 v103, 0, v103
	v_max_f32_e32 v66, v74, v74
	v_max_f32_e32 v67, v75, v75
	v_max_f32_e32 v68, v76, v76
	v_max_f32_e32 v69, v77, v77
	v_pk_mul_f32 v[2:3], v[2:3], v[2:3]
	v_pk_mul_f32 v[4:5], v[4:5], v[4:5]
	v_max_f32_e32 v0, v14, v14
	v_pk_mul_f32 v[116:117], v[116:117], v[116:117]
	v_pk_mul_f32 v[118:119], v[118:119], v[118:119]
	v_pk_mul_f32 v[100:101], v[100:101], v[100:101]
	v_pk_mul_f32 v[102:103], v[102:103], v[102:103]
	v_max_f32_e32 v66, 0, v66
	v_max_f32_e32 v67, 0, v67
	v_max_f32_e32 v68, 0, v68
	v_max_f32_e32 v69, 0, v69
	v_cvt_pk_bf16_f32 v2, v2, v3
	v_cvt_pk_bf16_f32 v3, v4, v5
	v_max_f32_e32 v4, 0, v0
	v_max_f32_e32 v0, v15, v15
	v_cvt_pk_bf16_f32 v116, v116, v117
	v_cvt_pk_bf16_f32 v117, v118, v119
	v_cvt_pk_bf16_f32 v100, v100, v101
	v_cvt_pk_bf16_f32 v101, v102, v103
	v_pk_mul_f32 v[66:67], v[66:67], v[66:67]
	v_pk_mul_f32 v[68:69], v[68:69], v[68:69]
	v_max_f32_e32 v5, 0, v0
	v_max_f32_e32 v0, v16, v16
	ds_write2_b64 v130, v[114:115], v[116:117] offset1:2
	v_max_f32_e32 v114, v122, v122
	v_max_f32_e32 v115, v123, v123
	v_max_f32_e32 v116, v124, v124
	v_max_f32_e32 v117, v125, v125
	ds_write2_b64 v130, v[98:99], v[100:101] offset0:8 offset1:10
	v_max_f32_e32 v98, v106, v106
	v_max_f32_e32 v99, v107, v107
	v_max_f32_e32 v100, v108, v108
	v_max_f32_e32 v101, v109, v109
	v_max_f32_e32 v82, v90, v90
	v_max_f32_e32 v83, v91, v91
	v_max_f32_e32 v84, v92, v92
	v_max_f32_e32 v85, v93, v93
	v_cvt_pk_bf16_f32 v66, v66, v67
	v_cvt_pk_bf16_f32 v67, v68, v69
	v_max_f32_e32 v68, v78, v78
	v_max_f32_e32 v69, v79, v79
	v_max_f32_e32 v70, v80, v80
	v_max_f32_e32 v71, v81, v81
	v_max_f32_e32 v50, v58, v58
	v_max_f32_e32 v51, v59, v59
	v_max_f32_e32 v52, v60, v60
	v_max_f32_e32 v53, v61, v61
	v_max_f32_e32 v6, 0, v0
	v_max_f32_e32 v0, v17, v17
	v_max_f32_e32 v114, 0, v114
	v_max_f32_e32 v115, 0, v115
	v_max_f32_e32 v116, 0, v116
	v_max_f32_e32 v117, 0, v117
	v_max_f32_e32 v98, 0, v98
	v_max_f32_e32 v99, 0, v99
	v_max_f32_e32 v100, 0, v100
	v_max_f32_e32 v101, 0, v101
	v_max_f32_e32 v82, 0, v82
	v_max_f32_e32 v83, 0, v83
	v_max_f32_e32 v84, 0, v84
	v_max_f32_e32 v85, 0, v85
	v_max_f32_e32 v68, 0, v68
	v_max_f32_e32 v69, 0, v69
	v_max_f32_e32 v70, 0, v70
	v_max_f32_e32 v71, 0, v71
	v_max_f32_e32 v50, 0, v50
	v_max_f32_e32 v51, 0, v51
	v_max_f32_e32 v52, 0, v52
	v_max_f32_e32 v53, 0, v53
	v_max_f32_e32 v7, 0, v0
	v_pk_mul_f32 v[114:115], v[114:115], v[114:115]
	v_pk_mul_f32 v[116:117], v[116:117], v[116:117]
	v_pk_mul_f32 v[98:99], v[98:99], v[98:99]
	v_pk_mul_f32 v[100:101], v[100:101], v[100:101]
	v_pk_mul_f32 v[82:83], v[82:83], v[82:83]
	v_pk_mul_f32 v[84:85], v[84:85], v[84:85]
	v_pk_mul_f32 v[68:69], v[68:69], v[68:69]
	v_pk_mul_f32 v[70:71], v[70:71], v[70:71]
	v_pk_mul_f32 v[50:51], v[50:51], v[50:51]
	v_pk_mul_f32 v[52:53], v[52:53], v[52:53]
	v_pk_mul_f32 v[4:5], v[4:5], v[4:5]
	v_pk_mul_f32 v[6:7], v[6:7], v[6:7]
	v_cvt_pk_bf16_f32 v114, v114, v115
	v_cvt_pk_bf16_f32 v115, v116, v117
	v_max_f32_e32 v116, v126, v126
	v_max_f32_e32 v117, v127, v127
	v_max_f32_e32 v118, v128, v128
	v_max_f32_e32 v119, v129, v129
	v_cvt_pk_bf16_f32 v98, v98, v99
	v_cvt_pk_bf16_f32 v99, v100, v101
	v_max_f32_e32 v100, v110, v110
	v_max_f32_e32 v101, v111, v111
	v_max_f32_e32 v102, v112, v112
	v_max_f32_e32 v103, v113, v113
	v_cvt_pk_bf16_f32 v82, v82, v83
	v_cvt_pk_bf16_f32 v83, v84, v85
	v_max_f32_e32 v84, v94, v94
	v_max_f32_e32 v85, v95, v95
	v_max_f32_e32 v86, v96, v96
	v_max_f32_e32 v87, v97, v97
	v_cvt_pk_bf16_f32 v68, v68, v69
	v_cvt_pk_bf16_f32 v69, v70, v71
	v_cvt_pk_bf16_f32 v50, v50, v51
	v_cvt_pk_bf16_f32 v51, v52, v53
	v_max_f32_e32 v52, v62, v62
	v_max_f32_e32 v53, v63, v63
	v_max_f32_e32 v54, v64, v64
	v_max_f32_e32 v55, v65, v65
	v_cvt_pk_bf16_f32 v4, v4, v5
	v_cvt_pk_bf16_f32 v5, v6, v7
	v_bfe_u32 v0, v138, 2, 8
	v_max_f32_e32 v116, 0, v116
	v_max_f32_e32 v117, 0, v117
	v_max_f32_e32 v118, 0, v118
	v_max_f32_e32 v119, 0, v119
	v_max_f32_e32 v100, 0, v100
	v_max_f32_e32 v101, 0, v101
	v_max_f32_e32 v102, 0, v102
	v_max_f32_e32 v103, 0, v103
	v_max_f32_e32 v84, 0, v84
	v_max_f32_e32 v85, 0, v85
	v_max_f32_e32 v86, 0, v86
	v_max_f32_e32 v87, 0, v87
	ds_write2_b64 v88, v[66:67], v[68:69] offset0:76 offset1:78
	v_max_f32_e32 v52, 0, v52
	v_max_f32_e32 v53, 0, v53
	v_max_f32_e32 v54, 0, v54
	v_max_f32_e32 v55, 0, v55
	ds_write2_b64 v34, v[2:3], v[4:5] offset0:12 offset1:14
	v_mul_u32_u24_e32 v5, 0x110, v0
	v_or_b32_e32 v0, s16, v0
	v_pk_mul_f32 v[116:117], v[116:117], v[116:117]
	v_pk_mul_f32 v[118:119], v[118:119], v[118:119]
	v_pk_mul_f32 v[100:101], v[100:101], v[100:101]
	v_pk_mul_f32 v[102:103], v[102:103], v[102:103]
	v_pk_mul_f32 v[84:85], v[84:85], v[84:85]
	v_pk_mul_f32 v[86:87], v[86:87], v[86:87]
	v_pk_mul_f32 v[52:53], v[52:53], v[52:53]
	v_pk_mul_f32 v[54:55], v[54:55], v[54:55]
	v_pk_mul_f32 v[20:21], v[20:21], v[20:21]
	v_pk_mul_f32 v[22:23], v[22:23], v[22:23]
	v_lshlrev_b32_e32 v0, 6, v0
	v_cvt_pk_bf16_f32 v116, v116, v117
	v_cvt_pk_bf16_f32 v117, v118, v119
	v_cvt_pk_bf16_f32 v100, v100, v101
	v_cvt_pk_bf16_f32 v101, v102, v103
	v_cvt_pk_bf16_f32 v84, v84, v85
	v_cvt_pk_bf16_f32 v85, v86, v87
	v_cvt_pk_bf16_f32 v52, v52, v53
	v_cvt_pk_bf16_f32 v53, v54, v55
	v_cvt_pk_bf16_f32 v20, v20, v21
	v_cvt_pk_bf16_f32 v21, v22, v23
	v_and_b32_e32 v4, 3, v138
	v_lshl_add_u64 v[2:3], s[92:93], 0, v[0:1]
	s_mov_b32 s18, 0
	ds_write2_b64 v130, v[114:115], v[116:117] offset0:4 offset1:6
	ds_write2_b64 v130, v[98:99], v[100:101] offset0:12 offset1:14
	ds_write2_b64 v88, v[82:83], v[84:85] offset0:68 offset1:70
	ds_write2_b64 v56, v[50:51], v[52:53] offset0:132 offset1:134
	ds_write2_b64 v34, v[18:19], v[20:21] offset0:4 offset1:6
	s_waitcnt lgkmcnt(0)
	s_barrier

.LBB0_1718:
	s_mul_i32 s18, s1, 0x6000
	v_add_u32_e32 v144, s18, v142
	v_add_u32_e32 v145, s18, v141
	v_add_u32_e32 v148, v144, v135
	v_add_u32_e32 v149, v145, v135
	v_add_u32_e32 v151, v144, v140
	v_add_u32_e32 v164, v145, v140
	s_waitcnt vmcnt(6)
	s_barrier
	ds_read_b128 v[144:147], v148
	ds_read_b128 v[152:155], v148 offset:2048
	ds_read_b128 v[156:159], v149
	ds_read_b128 v[160:163], v149 offset:2048
	ds_read_b128 v[170:173], v149 offset:4096
	ds_read_b128 v[174:177], v149 offset:6144
	ds_read_b128 v[178:181], v151
	ds_read_b128 v[182:185], v151 offset:2048
	ds_read_b128 v[186:189], v164
	ds_read_b128 v[190:193], v164 offset:2048
	ds_read_b128 v[194:197], v164 offset:4096
	ds_read_b128 v[198:201], v164 offset:6144
	s_waitcnt lgkmcnt(0)
	v_mfma_f32_32x32x16_bf16 v[114:129], v[144:147], v[156:159], v[114:129]
	s_waitcnt vmcnt(0)
	s_barrier
	v_mfma_f32_32x32x16_bf16 v[82:97], v[144:147], v[160:163], v[82:97]
	v_mfma_f32_32x32x16_bf16 v[50:65], v[144:147], v[170:173], v[50:65]
	v_mfma_f32_32x32x16_bf16 v[18:33], v[144:147], v[174:177], v[18:33]
	s_add_i32 s16, s18, 0xffffa000
	s_cmp_gt_i32 s1, 0
	s_cselect_b32 s16, s16, 0xc000
	v_add_u32_e32 v146, s16, v143
	v_lshl_add_u64 v[136:137], v[132:133], 0, v[0:1]
	s_mov_b64 s[16:17], 0x6500000
	v_lshl_add_u64 v[138:139], v[136:137], 0, s[16:17]
	v_readfirstlane_b32 s16, v146
	s_mov_b32 m0, s16
	s_mov_b64 s[16:17], 0x6501000
	v_add_u32_e32 v144, 0x1000, v146
	global_load_lds_dwordx4 v[138:139], off
	v_mfma_f32_32x32x16_bf16 v[98:113], v[152:155], v[156:159], v[98:113]
	v_lshl_add_u64 v[138:139], v[136:137], 0, s[16:17]
	v_readfirstlane_b32 s16, v144
	s_mov_b32 m0, s16
	s_mov_b64 s[16:17], 0x6502000
	v_add_u32_e32 v144, 0x2000, v146
	global_load_lds_dwordx4 v[138:139], off
	v_mfma_f32_32x32x16_bf16 v[66:81], v[152:155], v[160:163], v[66:81]
	v_lshl_add_u64 v[138:139], v[136:137], 0, s[16:17]
	v_readfirstlane_b32 s16, v144
	s_mov_b32 m0, s16
	s_mov_b64 s[16:17], 0x6503000
	v_add_u32_e32 v144, 0x3000, v146
	global_load_lds_dwordx4 v[138:139], off
	v_mfma_f32_32x32x16_bf16 v[34:49], v[152:155], v[170:173], v[34:49]
	v_lshl_add_u64 v[138:139], v[136:137], 0, s[16:17]
	v_readfirstlane_b32 s16, v144
	s_mov_b32 m0, s16
	s_mov_b64 s[16:17], 0x1920000
	global_load_lds_dwordx4 v[138:139], off
	v_mfma_f32_32x32x16_bf16 v[2:17], v[152:155], v[174:177], v[2:17]
	v_lshl_add_u64 v[138:139], v[130:131], 0, v[0:1]
	v_add_u32_e32 v147, 0x4000, v146
	v_lshl_add_u64 v[144:145], v[138:139], 0, s[16:17]
	v_readfirstlane_b32 s16, v147
	s_mov_b32 m0, s16
	s_mov_b64 s[16:17], 0x1921000
	v_add_u32_e32 v146, 0x5000, v146
	global_load_lds_dwordx4 v[144:145], off
	v_mfma_f32_32x32x16_bf16 v[114:129], v[178:181], v[186:189], v[114:129]
	v_lshl_add_u64 v[144:145], v[138:139], 0, s[16:17]
	v_readfirstlane_b32 s16, v146
	s_mov_b32 m0, s16
	s_add_i32 s16, s1, 1
	s_cmp_lg_u32 s1, 2
	s_cselect_b32 s1, s16, 0
	s_mul_i32 s16, s1, 0x6000
	s_add_i32 s17, s16, 0xffffa000
	global_load_lds_dwordx4 v[144:145], off
	v_mfma_f32_32x32x16_bf16 v[98:113], v[182:185], v[186:189], v[98:113]
	s_cmp_gt_i32 s1, 0
	s_cselect_b32 s17, s17, 0xc000
	s_mov_b64 s[18:19], 0x6700000
	v_lshl_add_u64 v[130:131], v[130:131], 0, s[58:59]
	v_lshl_add_u64 v[132:133], v[132:133], 0, s[96:97]
	v_add_u32_e32 v146, s17, v143
	v_add_u32_e32 v147, 0x1000, v146
	v_readfirstlane_b32 s17, v146
	v_lshl_add_u64 v[144:145], v[136:137], 0, s[18:19]
	s_mov_b32 m0, s17
	s_mov_b64 s[18:19], 0x6701000
	v_readfirstlane_b32 s17, v147
	v_add_u32_e32 v147, 0x2000, v146
	global_load_lds_dwordx4 v[144:145], off
	v_mfma_f32_32x32x16_bf16 v[82:97], v[178:181], v[190:193], v[82:97]
	v_lshl_add_u64 v[144:145], v[136:137], 0, s[18:19]
	s_mov_b32 m0, s17
	s_mov_b64 s[18:19], 0x6702000
	v_readfirstlane_b32 s17, v147
	global_load_lds_dwordx4 v[144:145], off
	v_mfma_f32_32x32x16_bf16 v[66:81], v[182:185], v[190:193], v[66:81]
	v_lshl_add_u64 v[144:145], v[136:137], 0, s[18:19]
	s_mov_b32 m0, s17
	s_mov_b64 s[18:19], 0x6703000
	global_load_lds_dwordx4 v[144:145], off
	v_mfma_f32_32x32x16_bf16 v[50:65], v[178:181], v[194:197], v[50:65]
	v_add_u32_e32 v144, 0x3000, v146
	v_lshl_add_u64 v[136:137], v[136:137], 0, s[18:19]
	v_readfirstlane_b32 s17, v144
	v_add_u32_e32 v144, 0x4000, v146
	s_mov_b32 m0, s17
	s_mov_b64 s[18:19], 0x1930000
	v_readfirstlane_b32 s17, v144
	global_load_lds_dwordx4 v[136:137], off
	v_mfma_f32_32x32x16_bf16 v[34:49], v[182:185], v[194:197], v[34:49]
	v_lshl_add_u64 v[136:137], v[138:139], 0, s[18:19]
	s_mov_b32 m0, s17
	s_mov_b64 s[18:19], 0x1931000
	global_load_lds_dwordx4 v[136:137], off
	v_mfma_f32_32x32x16_bf16 v[18:33], v[178:181], v[198:201], v[18:33]
	v_lshl_add_u64 v[136:137], v[138:139], 0, s[18:19]
	v_add_u32_e32 v138, 0x5000, v146
	s_nop 0
	v_readfirstlane_b32 s17, v138
	s_mov_b32 m0, s17
	s_nop 0
	global_load_lds_dwordx4 v[136:137], off
	v_mfma_f32_32x32x16_bf16 v[2:17], v[182:185], v[198:201], v[2:17]
	v_add_u32_e32 v136, s16, v142
	v_add_u32_e32 v137, s16, v141
	v_add_u32_e32 v148, v136, v135
	v_add_u32_e32 v149, v137, v135
	v_add_u32_e32 v151, v136, v140
	v_add_u32_e32 v164, v137, v140
	s_add_i32 s16, s1, 1
	s_cmp_lg_u32 s1, 2
	s_cselect_b32 s1, s16, 0
	s_add_i32 s0, s0, -2
	s_cmp_eq_u32 s0, 0
	ds_read_b128 v[136:139], v148
	ds_read_b128 v[144:147], v148 offset:2048
	ds_read_b128 v[152:155], v149
	ds_read_b128 v[156:159], v149 offset:2048
	ds_read_b128 v[160:163], v149 offset:4096
	ds_read_b128 v[170:173], v149 offset:6144
	ds_read_b128 v[174:177], v151
	ds_read_b128 v[178:181], v151 offset:2048
	ds_read_b128 v[182:185], v164
	ds_read_b128 v[186:189], v164 offset:2048
	ds_read_b128 v[190:193], v164 offset:4096
	ds_read_b128 v[194:197], v164 offset:6144
	s_waitcnt lgkmcnt(0)
	s_nop 0
	v_mfma_f32_32x32x16_bf16 v[114:129], v[136:139], v[152:155], v[114:129]
	v_mfma_f32_32x32x16_bf16 v[98:113], v[144:147], v[152:155], v[98:113]
	v_mfma_f32_32x32x16_bf16 v[82:97], v[136:139], v[156:159], v[82:97]
	v_mfma_f32_32x32x16_bf16 v[66:81], v[144:147], v[156:159], v[66:81]
	v_mfma_f32_32x32x16_bf16 v[50:65], v[136:139], v[160:163], v[50:65]
	v_mfma_f32_32x32x16_bf16 v[34:49], v[144:147], v[160:163], v[34:49]
	v_mfma_f32_32x32x16_bf16 v[18:33], v[136:139], v[170:173], v[18:33]
	v_mfma_f32_32x32x16_bf16 v[2:17], v[144:147], v[170:173], v[2:17]
	v_mfma_f32_32x32x16_bf16 v[114:129], v[174:177], v[182:185], v[114:129]
	v_mfma_f32_32x32x16_bf16 v[98:113], v[178:181], v[182:185], v[98:113]
	v_mfma_f32_32x32x16_bf16 v[82:97], v[174:177], v[186:189], v[82:97]
	v_mfma_f32_32x32x16_bf16 v[66:81], v[178:181], v[186:189], v[66:81]
	v_mfma_f32_32x32x16_bf16 v[50:65], v[174:177], v[190:193], v[50:65]
	v_mfma_f32_32x32x16_bf16 v[34:49], v[178:181], v[190:193], v[34:49]
	v_mfma_f32_32x32x16_bf16 v[18:33], v[174:177], v[194:197], v[18:33]
	v_mfma_f32_32x32x16_bf16 v[2:17], v[178:181], v[194:197], v[2:17]
	s_cbranch_scc0 .LBB0_1718
	s_mul_i32 s0, s1, 0x6000
	v_add_u32_e32 v0, s0, v142
	v_add_u32_e32 v130, s0, v141
	s_waitcnt vmcnt(6)
	s_barrier
	v_add_u32_e32 v143, v0, v135
	v_add_u32_e32 v148, v130, v135
	v_add_u32_e32 v0, v0, v140
	v_add_u32_e32 v149, v130, v140
	ds_read_b128 v[130:133], v143
	ds_read_b128 v[136:139], v143 offset:2048
	ds_read_b128 v[144:147], v148
	ds_read_b128 v[152:155], v148 offset:2048
	ds_read_b128 v[156:159], v148 offset:4096
	ds_read_b128 v[160:163], v148 offset:6144
	ds_read_b128 v[170:173], v0
	ds_read_b128 v[174:177], v0 offset:2048
	ds_read_b128 v[178:181], v149
	ds_read_b128 v[182:185], v149 offset:2048
	ds_read_b128 v[186:189], v149 offset:4096
	ds_read_b128 v[190:193], v149 offset:6144
	s_waitcnt lgkmcnt(0)
	s_addk_i32 s0, 0x6000
	v_mfma_f32_32x32x16_bf16 v[114:129], v[130:133], v[144:147], v[114:129]
	s_cmp_lg_u32 s1, 2
	s_cselect_b32 s0, s0, 0
	v_add_u32_e32 v0, s0, v142
	s_waitcnt vmcnt(0)
	s_barrier
	v_add_u32_e32 v148, v0, v135
	v_add_u32_e32 v0, v0, v140
	v_mfma_f32_32x32x16_bf16 v[98:113], v[136:139], v[144:147], v[98:113]
	v_mfma_f32_32x32x16_bf16 v[82:97], v[130:133], v[152:155], v[82:97]
	v_mfma_f32_32x32x16_bf16 v[66:81], v[136:139], v[152:155], v[66:81]
	v_mfma_f32_32x32x16_bf16 v[50:65], v[130:133], v[156:159], v[50:65]
	v_mfma_f32_32x32x16_bf16 v[34:49], v[136:139], v[156:159], v[34:49]
	v_mfma_f32_32x32x16_bf16 v[18:33], v[130:133], v[160:163], v[18:33]
	v_add_u32_e32 v130, s0, v141
	v_add_u32_e32 v135, v130, v135
	v_add_u32_e32 v149, v130, v140
	s_movk_i32 s0, 0x80
	v_cmp_gt_u32_e64 s[48:49], s0, v134
	v_mfma_f32_32x32x16_bf16 v[2:17], v[136:139], v[160:163], v[2:17]
	v_mfma_f32_32x32x16_bf16 v[114:129], v[170:173], v[178:181], v[114:129]
	v_mfma_f32_32x32x16_bf16 v[98:113], v[174:177], v[178:181], v[98:113]
	v_mfma_f32_32x32x16_bf16 v[82:97], v[170:173], v[182:185], v[82:97]
	v_mfma_f32_32x32x16_bf16 v[66:81], v[174:177], v[182:185], v[66:81]
	v_mfma_f32_32x32x16_bf16 v[50:65], v[170:173], v[186:189], v[50:65]
	v_mfma_f32_32x32x16_bf16 v[34:49], v[174:177], v[186:189], v[34:49]
	v_mfma_f32_32x32x16_bf16 v[18:33], v[170:173], v[190:193], v[18:33]
	v_mfma_f32_32x32x16_bf16 v[2:17], v[174:177], v[190:193], v[2:17]
	ds_read_b128 v[130:133], v148
	ds_read_b128 v[136:139], v148 offset:2048
	ds_read_b128 v[140:143], v135
	ds_read_b128 v[144:147], v135 offset:2048
	ds_read_b128 v[152:155], v135 offset:4096
	ds_read_b128 v[156:159], v135 offset:6144
	ds_read_b128 v[160:163], v0
	ds_read_b128 v[170:173], v0 offset:2048
	ds_read_b128 v[174:177], v149
	ds_read_b128 v[178:181], v149 offset:2048
	ds_read_b128 v[182:185], v149 offset:4096
	ds_read_b128 v[186:189], v149 offset:6144
	s_waitcnt lgkmcnt(0)
	s_waitcnt vmcnt(0) lgkmcnt(0)
	s_barrier
	v_mfma_f32_32x32x16_bf16 v[114:129], v[130:133], v[140:143], v[114:129]
	v_mfma_f32_32x32x16_bf16 v[98:113], v[136:139], v[140:143], v[98:113]
	v_mfma_f32_32x32x16_bf16 v[82:97], v[130:133], v[144:147], v[82:97]
	v_mfma_f32_32x32x16_bf16 v[66:81], v[136:139], v[144:147], v[66:81]
	v_mfma_f32_32x32x16_bf16 v[50:65], v[130:133], v[152:155], v[50:65]
	v_mfma_f32_32x32x16_bf16 v[34:49], v[136:139], v[152:155], v[34:49]
	v_and_b32_e32 v153, 31, v134
	v_mfma_f32_32x32x16_bf16 v[18:33], v[130:133], v[156:159], v[18:33]
	v_mfma_f32_32x32x16_bf16 v[2:17], v[136:139], v[156:159], v[2:17]
	v_and_b32_e32 v137, 64, v134
	v_mfma_f32_32x32x16_bf16 v[114:129], v[160:163], v[174:177], v[114:129]
	v_mfma_f32_32x32x16_bf16 v[98:113], v[170:173], v[174:177], v[98:113]
	v_mfma_f32_32x32x16_bf16 v[82:97], v[160:163], v[178:181], v[82:97]
	v_mfma_f32_32x32x16_bf16 v[66:81], v[170:173], v[178:181], v[66:81]
	v_mfma_f32_32x32x16_bf16 v[50:65], v[160:163], v[182:185], v[50:65]
	v_mfma_f32_32x32x16_bf16 v[34:49], v[170:173], v[182:185], v[34:49]
	v_mfma_f32_32x32x16_bf16 v[18:33], v[160:163], v[186:189], v[18:33]
	v_mfma_f32_32x32x16_bf16 v[2:17], v[170:173], v[186:189], v[2:17]
	s_and_saveexec_b64 s[0:1], s[48:49]
	s_cbranch_execz .LBB0_1721
	v_mul_u32_u24_e32 v0, 0x210, v153
	v_lshlrev_b32_e32 v130, 4, v150
	v_lshlrev_b32_e32 v131, 2, v137
	v_add3_u32 v0, v0, v130, v131
	ds_write_b128 v0, v[114:117]
	ds_write_b128 v0, v[118:121] offset:32
	ds_write_b128 v0, v[122:125] offset:64
	ds_write_b128 v0, v[126:129] offset:96
	ds_write_b128 v0, v[98:101] offset:128
	ds_write_b128 v0, v[102:105] offset:160
	ds_write_b128 v0, v[106:109] offset:192
	ds_write_b128 v0, v[110:113] offset:224
	ds_write_b128 v0, v[82:85] offset:16896
	ds_write_b128 v0, v[86:89] offset:16928
	ds_write_b128 v0, v[90:93] offset:16960
	ds_write_b128 v0, v[94:97] offset:16992
	ds_write_b128 v0, v[66:69] offset:17024
	ds_write_b128 v0, v[70:73] offset:17056
	ds_write_b128 v0, v[74:77] offset:17088
	ds_write_b128 v0, v[78:81] offset:17120
	ds_write_b128 v0, v[50:53] offset:33792
	ds_write_b128 v0, v[54:57] offset:33824
	ds_write_b128 v0, v[58:61] offset:33856
	ds_write_b128 v0, v[62:65] offset:33888
	ds_write_b128 v0, v[34:37] offset:33920
	ds_write_b128 v0, v[38:41] offset:33952
	ds_write_b128 v0, v[42:45] offset:33984
	ds_write_b128 v0, v[46:49] offset:34016
	v_or_b32_e32 v0, 0x60, v134
	v_mul_lo_u32 v0, v0, s94
	v_add3_u32 v0, v0, v130, v131
	ds_write_b128 v0, v[18:21]
	ds_write_b128 v0, v[22:25] offset:32
	ds_write_b128 v0, v[26:29] offset:64
	ds_write_b128 v0, v[30:33] offset:96
	ds_write_b128 v0, v[2:5] offset:128
	ds_write_b128 v0, v[6:9] offset:160
	ds_write_b128 v0, v[10:13] offset:192
	ds_write_b128 v0, v[14:17] offset:224
